# saddr + LDS-DMA group issued before the ds_reads in each load segment of the GEMM K-loops
# baseline (speedup 1.0000x reference)
.LBB0_109:
	s_add_u32 s22, s20, 0xfff04000
	s_addc_u32 s23, s21, -1
	s_cmp_eq_u32 s46, 60
	s_cselect_b32 s26, s42, s22
	s_cselect_b32 s27, s15, s23
	s_cselect_b32 s24, s43, s44
	s_cselect_b32 s25, s13, s45
	s_add_u32 s22, s26, 0x4000
	s_addc_u32 s23, s27, 0
	s_add_i32 m0, s29, 0xc000
	s_nop 0
	global_load_lds_dwordx4 v146, s[20:21]
	s_add_i32 m0, s29, 0xe000
	s_nop 0
	global_load_lds_dwordx4 v148, s[20:21]
	ds_read_b128 v[130:133], v158
	ds_read_b128 v[162:165], v158 offset:1024
	ds_read_b128 v[166:169], v158 offset:2048
	ds_read_b128 v[170:173], v158 offset:3072
	ds_read_b128 v[174:177], v159
	ds_read_b128 v[178:181], v159 offset:1024
	ds_read_b128 v[182:185], v159 offset:2048
	ds_read_b128 v[186:189], v159 offset:3072
	ds_read_b128 v[190:193], v160
	ds_read_b128 v[194:197], v160 offset:1024
	ds_read_b128 v[198:201], v160 offset:2048
	ds_read_b128 v[202:205], v160 offset:3072
	ds_read_b128 v[206:209], v160 offset:4096
	ds_read_b128 v[210:213], v160 offset:5120
	ds_read_b128 v[214:217], v160 offset:6144
	ds_read_b128 v[218:221], v160 offset:7168
	s_waitcnt vmcnt(8)
	s_waitcnt lgkmcnt(0)
	s_barrier
	s_setprio 1
	s_waitcnt lgkmcnt(0)
	v_mfma_f32_16x16x32_bf16 v[62:65], v[130:133], v[190:193], v[62:65]
	v_mfma_f32_16x16x32_bf16 v[58:61], v[166:169], v[190:193], v[58:61]
	v_mfma_f32_16x16x32_bf16 v[54:57], v[130:133], v[198:201], v[54:57]
	v_mfma_f32_16x16x32_bf16 v[50:53], v[166:169], v[198:201], v[50:53]
	v_mfma_f32_16x16x32_bf16 v[46:49], v[130:133], v[206:209], v[46:49]
	v_mfma_f32_16x16x32_bf16 v[42:45], v[166:169], v[206:209], v[42:45]
	v_mfma_f32_16x16x32_bf16 v[38:41], v[130:133], v[214:217], v[38:41]
	v_mfma_f32_16x16x32_bf16 v[34:37], v[166:169], v[214:217], v[34:37]
	v_mfma_f32_16x16x32_bf16 v[62:65], v[162:165], v[194:197], v[62:65]
	v_mfma_f32_16x16x32_bf16 v[58:61], v[170:173], v[194:197], v[58:61]
	v_mfma_f32_16x16x32_bf16 v[54:57], v[162:165], v[202:205], v[54:57]
	v_mfma_f32_16x16x32_bf16 v[50:53], v[170:173], v[202:205], v[50:53]
	v_mfma_f32_16x16x32_bf16 v[46:49], v[162:165], v[210:213], v[46:49]
	v_mfma_f32_16x16x32_bf16 v[42:45], v[170:173], v[210:213], v[42:45]
	v_mfma_f32_16x16x32_bf16 v[38:41], v[162:165], v[218:221], v[38:41]
	v_mfma_f32_16x16x32_bf16 v[34:37], v[170:173], v[218:221], v[34:37]
	s_setprio 0
	s_setprio 1
	v_mfma_f32_16x16x32_bf16 v[126:129], v[174:177], v[190:193], v[126:129]
	v_mfma_f32_16x16x32_bf16 v[122:125], v[182:185], v[190:193], v[122:125]
	v_mfma_f32_16x16x32_bf16 v[118:121], v[174:177], v[198:201], v[118:121]
	v_mfma_f32_16x16x32_bf16 v[114:117], v[182:185], v[198:201], v[114:117]
	v_mfma_f32_16x16x32_bf16 v[110:113], v[174:177], v[206:209], v[110:113]
	v_mfma_f32_16x16x32_bf16 v[106:109], v[182:185], v[206:209], v[106:109]
	v_mfma_f32_16x16x32_bf16 v[102:105], v[174:177], v[214:217], v[102:105]
	v_mfma_f32_16x16x32_bf16 v[98:101], v[182:185], v[214:217], v[98:101]
	v_mfma_f32_16x16x32_bf16 v[126:129], v[178:181], v[194:197], v[126:129]
	v_mfma_f32_16x16x32_bf16 v[122:125], v[186:189], v[194:197], v[122:125]
	v_mfma_f32_16x16x32_bf16 v[118:121], v[178:181], v[202:205], v[118:121]
	v_mfma_f32_16x16x32_bf16 v[114:117], v[186:189], v[202:205], v[114:117]
	v_mfma_f32_16x16x32_bf16 v[110:113], v[178:181], v[210:213], v[110:113]
	v_mfma_f32_16x16x32_bf16 v[106:109], v[186:189], v[210:213], v[106:109]
	v_mfma_f32_16x16x32_bf16 v[102:105], v[178:181], v[218:221], v[102:105]
	v_mfma_f32_16x16x32_bf16 v[98:101], v[186:189], v[218:221], v[98:101]
	s_setprio 0
	s_barrier
	s_add_i32 s47, s36, s28
	s_mov_b32 m0, s47
	s_nop 0
	global_load_lds_dwordx4 v138, s[24:25]
	s_add_i32 m0, s47, 0x2000
	s_add_u32 s48, s24, 0x100000
	s_addc_u32 s49, s25, 0
	s_add_i32 s47, s37, s28
	global_load_lds_dwordx4 v134, s[24:25]
	s_mov_b32 m0, s47
	s_nop 0
	global_load_lds_dwordx4 v138, s[48:49]
	s_add_i32 m0, s47, 0x2000
	s_nop 0
	global_load_lds_dwordx4 v134, s[48:49]
	s_mov_b32 m0, s29
	s_nop 0
	global_load_lds_dwordx4 v140, s[26:27]
	s_mov_b32 m0, s30
	s_nop 0
	global_load_lds_dwordx4 v136, s[26:27]
	ds_read_b128 v[190:193], v160 offset:16384
	ds_read_b128 v[194:197], v160 offset:17408
	ds_read_b128 v[198:201], v160 offset:18432
	ds_read_b128 v[202:205], v160 offset:19456
	ds_read_b128 v[206:209], v160 offset:20480
	ds_read_b128 v[210:213], v160 offset:21504
	ds_read_b128 v[214:217], v160 offset:22528
	ds_read_b128 v[218:221], v160 offset:23552
	s_waitcnt vmcnt(8)
	s_waitcnt lgkmcnt(0)
	s_barrier
	s_setprio 1
	s_waitcnt lgkmcnt(0)
	v_mfma_f32_16x16x32_bf16 v[30:33], v[130:133], v[190:193], v[30:33]
	v_mfma_f32_16x16x32_bf16 v[26:29], v[166:169], v[190:193], v[26:29]
	v_mfma_f32_16x16x32_bf16 v[22:25], v[130:133], v[198:201], v[22:25]
	v_mfma_f32_16x16x32_bf16 v[18:21], v[166:169], v[198:201], v[18:21]
	v_mfma_f32_16x16x32_bf16 v[14:17], v[130:133], v[206:209], v[14:17]
	v_mfma_f32_16x16x32_bf16 v[10:13], v[166:169], v[206:209], v[10:13]
	v_mfma_f32_16x16x32_bf16 v[6:9], v[130:133], v[214:217], v[6:9]
	v_mfma_f32_16x16x32_bf16 v[2:5], v[166:169], v[214:217], v[2:5]
	v_mfma_f32_16x16x32_bf16 v[30:33], v[162:165], v[194:197], v[30:33]
	v_mfma_f32_16x16x32_bf16 v[26:29], v[170:173], v[194:197], v[26:29]
	v_mfma_f32_16x16x32_bf16 v[22:25], v[162:165], v[202:205], v[22:25]
	v_mfma_f32_16x16x32_bf16 v[18:21], v[170:173], v[202:205], v[18:21]
	v_mfma_f32_16x16x32_bf16 v[14:17], v[162:165], v[210:213], v[14:17]
	v_mfma_f32_16x16x32_bf16 v[10:13], v[170:173], v[210:213], v[10:13]
	v_mfma_f32_16x16x32_bf16 v[6:9], v[162:165], v[218:221], v[6:9]
	v_mfma_f32_16x16x32_bf16 v[2:5], v[170:173], v[218:221], v[2:5]
	s_setprio 0
	s_setprio 1
	v_mfma_f32_16x16x32_bf16 v[94:97], v[174:177], v[190:193], v[94:97]
	v_mfma_f32_16x16x32_bf16 v[90:93], v[182:185], v[190:193], v[90:93]
	v_mfma_f32_16x16x32_bf16 v[86:89], v[174:177], v[198:201], v[86:89]
	v_mfma_f32_16x16x32_bf16 v[82:85], v[182:185], v[198:201], v[82:85]
	v_mfma_f32_16x16x32_bf16 v[78:81], v[174:177], v[206:209], v[78:81]
	v_mfma_f32_16x16x32_bf16 v[74:77], v[182:185], v[206:209], v[74:77]
	v_mfma_f32_16x16x32_bf16 v[70:73], v[174:177], v[214:217], v[70:73]
	v_mfma_f32_16x16x32_bf16 v[66:69], v[182:185], v[214:217], v[66:69]
	v_mfma_f32_16x16x32_bf16 v[94:97], v[178:181], v[194:197], v[94:97]
	v_mfma_f32_16x16x32_bf16 v[90:93], v[186:189], v[194:197], v[90:93]
	v_mfma_f32_16x16x32_bf16 v[86:89], v[178:181], v[202:205], v[86:89]
	v_mfma_f32_16x16x32_bf16 v[82:85], v[186:189], v[202:205], v[82:85]
	v_mfma_f32_16x16x32_bf16 v[78:81], v[178:181], v[210:213], v[78:81]
	v_mfma_f32_16x16x32_bf16 v[74:77], v[186:189], v[210:213], v[74:77]
	v_mfma_f32_16x16x32_bf16 v[70:73], v[178:181], v[218:221], v[70:73]
	v_mfma_f32_16x16x32_bf16 v[66:69], v[186:189], v[218:221], v[66:69]
	s_setprio 0
	s_barrier
	s_add_i32 s47, 0, 0x18000
	s_add_i32 s48, 0, 0x1c000
	s_add_u32 s26, s26, 0x100000
	s_addc_u32 s27, s27, 0
	s_mov_b32 m0, s31
	s_nop 0
	global_load_lds_dwordx4 v140, s[26:27]
	s_mov_b32 m0, s33
	s_nop 0
	global_load_lds_dwordx4 v136, s[26:27]
	v_add_u32_e32 v154, s47, v156
	ds_read_b128 v[130:133], v154
	ds_read_b128 v[162:165], v154 offset:1024
	ds_read_b128 v[166:169], v154 offset:2048
	ds_read_b128 v[170:173], v154 offset:3072
	v_add_u32_e32 v154, s48, v156
	ds_read_b128 v[174:177], v154
	ds_read_b128 v[178:181], v154 offset:1024
	ds_read_b128 v[182:185], v154 offset:2048
	ds_read_b128 v[186:189], v154 offset:3072
	ds_read_b128 v[190:193], v160 offset:32768
	ds_read_b128 v[194:197], v160 offset:33792
	ds_read_b128 v[198:201], v160 offset:34816
	ds_read_b128 v[202:205], v160 offset:35840
	ds_read_b128 v[206:209], v160 offset:36864
	ds_read_b128 v[210:213], v160 offset:37888
	ds_read_b128 v[214:217], v160 offset:38912
	ds_read_b128 v[218:221], v160 offset:39936
	s_waitcnt vmcnt(8)
	s_waitcnt lgkmcnt(0)
	s_barrier
	s_setprio 1
	s_waitcnt lgkmcnt(0)
	v_mfma_f32_16x16x32_bf16 v[62:65], v[130:133], v[190:193], v[62:65]
	v_mfma_f32_16x16x32_bf16 v[58:61], v[166:169], v[190:193], v[58:61]
	v_mfma_f32_16x16x32_bf16 v[54:57], v[130:133], v[198:201], v[54:57]
	v_mfma_f32_16x16x32_bf16 v[50:53], v[166:169], v[198:201], v[50:53]
	v_mfma_f32_16x16x32_bf16 v[46:49], v[130:133], v[206:209], v[46:49]
	v_mfma_f32_16x16x32_bf16 v[42:45], v[166:169], v[206:209], v[42:45]
	v_mfma_f32_16x16x32_bf16 v[38:41], v[130:133], v[214:217], v[38:41]
	v_mfma_f32_16x16x32_bf16 v[34:37], v[166:169], v[214:217], v[34:37]
	v_mfma_f32_16x16x32_bf16 v[62:65], v[162:165], v[194:197], v[62:65]
	v_mfma_f32_16x16x32_bf16 v[58:61], v[170:173], v[194:197], v[58:61]
	v_mfma_f32_16x16x32_bf16 v[54:57], v[162:165], v[202:205], v[54:57]
	v_mfma_f32_16x16x32_bf16 v[50:53], v[170:173], v[202:205], v[50:53]
	v_mfma_f32_16x16x32_bf16 v[46:49], v[162:165], v[210:213], v[46:49]
	v_mfma_f32_16x16x32_bf16 v[42:45], v[170:173], v[210:213], v[42:45]
	v_mfma_f32_16x16x32_bf16 v[38:41], v[162:165], v[218:221], v[38:41]
	v_mfma_f32_16x16x32_bf16 v[34:37], v[170:173], v[218:221], v[34:37]
	s_setprio 0
	s_setprio 1
	v_mfma_f32_16x16x32_bf16 v[126:129], v[174:177], v[190:193], v[126:129]
	v_mfma_f32_16x16x32_bf16 v[122:125], v[182:185], v[190:193], v[122:125]
	v_mfma_f32_16x16x32_bf16 v[118:121], v[174:177], v[198:201], v[118:121]
	v_mfma_f32_16x16x32_bf16 v[114:117], v[182:185], v[198:201], v[114:117]
	v_mfma_f32_16x16x32_bf16 v[110:113], v[174:177], v[206:209], v[110:113]
	v_mfma_f32_16x16x32_bf16 v[106:109], v[182:185], v[206:209], v[106:109]
	v_mfma_f32_16x16x32_bf16 v[102:105], v[174:177], v[214:217], v[102:105]
	v_mfma_f32_16x16x32_bf16 v[98:101], v[182:185], v[214:217], v[98:101]
	v_mfma_f32_16x16x32_bf16 v[126:129], v[178:181], v[194:197], v[126:129]
	v_mfma_f32_16x16x32_bf16 v[122:125], v[186:189], v[194:197], v[122:125]
	v_mfma_f32_16x16x32_bf16 v[118:121], v[178:181], v[202:205], v[118:121]
	v_mfma_f32_16x16x32_bf16 v[114:117], v[186:189], v[202:205], v[114:117]
	v_mfma_f32_16x16x32_bf16 v[110:113], v[178:181], v[210:213], v[110:113]
	v_mfma_f32_16x16x32_bf16 v[106:109], v[186:189], v[210:213], v[106:109]
	v_mfma_f32_16x16x32_bf16 v[102:105], v[178:181], v[218:221], v[102:105]
	v_mfma_f32_16x16x32_bf16 v[98:101], v[186:189], v[218:221], v[98:101]
	s_setprio 0
	s_barrier
	s_add_u32 s26, s24, 0x4000
	s_addc_u32 s27, s25, 0
	s_add_i32 s47, s47, s28
	s_mov_b32 m0, s47
	s_nop 0
	global_load_lds_dwordx4 v138, s[26:27]
	s_add_i32 m0, s47, 0x2000
	s_add_u32 s24, s24, 0x104000
	s_addc_u32 s25, s25, 0
	global_load_lds_dwordx4 v134, s[26:27]
	s_add_i32 s26, s48, s28
	s_mov_b32 m0, s26
	s_nop 0
	global_load_lds_dwordx4 v138, s[24:25]
	s_add_i32 m0, s26, 0x2000
	s_nop 0
	global_load_lds_dwordx4 v134, s[24:25]
	s_mov_b32 m0, s34
	s_nop 0
	global_load_lds_dwordx4 v140, s[22:23]
	s_mov_b32 m0, s35
	s_nop 0
	global_load_lds_dwordx4 v136, s[22:23]
	ds_read_b128 v[190:193], v160 offset:49152
	ds_read_b128 v[194:197], v160 offset:50176
	ds_read_b128 v[198:201], v160 offset:51200
	ds_read_b128 v[202:205], v160 offset:52224
	ds_read_b128 v[206:209], v160 offset:53248
	ds_read_b128 v[210:213], v160 offset:54272
	ds_read_b128 v[214:217], v160 offset:55296
	ds_read_b128 v[218:221], v160 offset:56320
	s_waitcnt vmcnt(8)
	s_waitcnt lgkmcnt(0)
	s_barrier
	s_setprio 1
	s_waitcnt lgkmcnt(0)
	v_mfma_f32_16x16x32_bf16 v[30:33], v[130:133], v[190:193], v[30:33]
	v_mfma_f32_16x16x32_bf16 v[26:29], v[166:169], v[190:193], v[26:29]
	v_mfma_f32_16x16x32_bf16 v[22:25], v[130:133], v[198:201], v[22:25]
	v_mfma_f32_16x16x32_bf16 v[18:21], v[166:169], v[198:201], v[18:21]
	v_mfma_f32_16x16x32_bf16 v[14:17], v[130:133], v[206:209], v[14:17]
	v_mfma_f32_16x16x32_bf16 v[10:13], v[166:169], v[206:209], v[10:13]
	v_mfma_f32_16x16x32_bf16 v[6:9], v[130:133], v[214:217], v[6:9]
	v_mfma_f32_16x16x32_bf16 v[2:5], v[166:169], v[214:217], v[2:5]
	v_mfma_f32_16x16x32_bf16 v[30:33], v[162:165], v[194:197], v[30:33]
	v_mfma_f32_16x16x32_bf16 v[26:29], v[170:173], v[194:197], v[26:29]
	v_mfma_f32_16x16x32_bf16 v[22:25], v[162:165], v[202:205], v[22:25]
	v_mfma_f32_16x16x32_bf16 v[18:21], v[170:173], v[202:205], v[18:21]
	v_mfma_f32_16x16x32_bf16 v[14:17], v[162:165], v[210:213], v[14:17]
	v_mfma_f32_16x16x32_bf16 v[10:13], v[170:173], v[210:213], v[10:13]
	v_mfma_f32_16x16x32_bf16 v[6:9], v[162:165], v[218:221], v[6:9]
	v_mfma_f32_16x16x32_bf16 v[2:5], v[170:173], v[218:221], v[2:5]
	s_setprio 0
	s_setprio 1
	v_mfma_f32_16x16x32_bf16 v[94:97], v[174:177], v[190:193], v[94:97]
	v_mfma_f32_16x16x32_bf16 v[90:93], v[182:185], v[190:193], v[90:93]
	v_mfma_f32_16x16x32_bf16 v[86:89], v[174:177], v[198:201], v[86:89]
	v_mfma_f32_16x16x32_bf16 v[82:85], v[182:185], v[198:201], v[82:85]
	v_mfma_f32_16x16x32_bf16 v[78:81], v[174:177], v[206:209], v[78:81]
	v_mfma_f32_16x16x32_bf16 v[74:77], v[182:185], v[206:209], v[74:77]
	v_mfma_f32_16x16x32_bf16 v[70:73], v[174:177], v[214:217], v[70:73]
	v_mfma_f32_16x16x32_bf16 v[66:69], v[182:185], v[214:217], v[66:69]
	v_mfma_f32_16x16x32_bf16 v[94:97], v[178:181], v[194:197], v[94:97]
	v_mfma_f32_16x16x32_bf16 v[90:93], v[186:189], v[194:197], v[90:93]
	v_mfma_f32_16x16x32_bf16 v[86:89], v[178:181], v[202:205], v[86:89]
	v_mfma_f32_16x16x32_bf16 v[82:85], v[186:189], v[202:205], v[82:85]
	v_mfma_f32_16x16x32_bf16 v[78:81], v[178:181], v[210:213], v[78:81]
	v_mfma_f32_16x16x32_bf16 v[74:77], v[186:189], v[210:213], v[74:77]
	v_mfma_f32_16x16x32_bf16 v[70:73], v[178:181], v[218:221], v[70:73]
	v_mfma_f32_16x16x32_bf16 v[66:69], v[186:189], v[218:221], v[66:69]
	s_setprio 0
	s_barrier
	s_add_i32 s46, s46, 2
	s_add_u32 s20, s20, 0x8000
	s_addc_u32 s21, s21, 0
	s_add_u32 s44, s44, 0x8000
	s_addc_u32 s45, s45, 0
	s_cmp_gt_u32 s46, 61
	s_cbranch_scc0 .LBB0_109
	s_and_b64 vcc, exec, s[8:9]
	s_cbranch_vccnz .LBB0_113
	v_lshl_add_u32 v154, s4, 8, v1
	s_cmp_lg_u32 s41, 24
	s_mov_b64 s[20:21], -1
	s_cbranch_scc1 .LBB0_114

.LBB0_376:
	s_add_u32 s34, s26, 0xfff04000
	s_addc_u32 s35, s27, -1
	s_cmp_eq_u32 s87, 60
	s_cselect_b32 s38, s80, s34
	s_cselect_b32 s39, s21, s35
	s_cselect_b32 s36, s81, s83
	s_cselect_b32 s37, s19, s86
	s_add_u32 s34, s38, 0x4000
	s_addc_u32 s35, s39, 0
	s_add_i32 m0, s46, 0xc000
	s_nop 0
	global_load_lds_dwordx4 v146, s[26:27]
	s_add_i32 m0, s46, 0xe000
	s_nop 0
	global_load_lds_dwordx4 v148, s[26:27]
	ds_read_b128 v[130:133], v159
	ds_read_b128 v[162:165], v159 offset:1024
	ds_read_b128 v[166:169], v159 offset:2048
	ds_read_b128 v[170:173], v159 offset:3072
	ds_read_b128 v[174:177], v160
	ds_read_b128 v[178:181], v160 offset:1024
	ds_read_b128 v[182:185], v160 offset:2048
	ds_read_b128 v[186:189], v160 offset:3072
	ds_read_b128 v[190:193], v161
	ds_read_b128 v[194:197], v161 offset:1024
	ds_read_b128 v[198:201], v161 offset:2048
	ds_read_b128 v[202:205], v161 offset:3072
	ds_read_b128 v[206:209], v161 offset:4096
	ds_read_b128 v[210:213], v161 offset:5120
	ds_read_b128 v[214:217], v161 offset:6144
	ds_read_b128 v[218:221], v161 offset:7168
	s_waitcnt vmcnt(8)
	s_waitcnt lgkmcnt(0)
	s_barrier
	s_setprio 1
	s_waitcnt lgkmcnt(0)
	v_mfma_f32_16x16x32_bf16 v[62:65], v[130:133], v[190:193], v[62:65]
	v_mfma_f32_16x16x32_bf16 v[58:61], v[166:169], v[190:193], v[58:61]
	v_mfma_f32_16x16x32_bf16 v[54:57], v[130:133], v[198:201], v[54:57]
	v_mfma_f32_16x16x32_bf16 v[50:53], v[166:169], v[198:201], v[50:53]
	v_mfma_f32_16x16x32_bf16 v[46:49], v[130:133], v[206:209], v[46:49]
	v_mfma_f32_16x16x32_bf16 v[42:45], v[166:169], v[206:209], v[42:45]
	v_mfma_f32_16x16x32_bf16 v[38:41], v[130:133], v[214:217], v[38:41]
	v_mfma_f32_16x16x32_bf16 v[34:37], v[166:169], v[214:217], v[34:37]
	v_mfma_f32_16x16x32_bf16 v[62:65], v[162:165], v[194:197], v[62:65]
	v_mfma_f32_16x16x32_bf16 v[58:61], v[170:173], v[194:197], v[58:61]
	v_mfma_f32_16x16x32_bf16 v[54:57], v[162:165], v[202:205], v[54:57]
	v_mfma_f32_16x16x32_bf16 v[50:53], v[170:173], v[202:205], v[50:53]
	v_mfma_f32_16x16x32_bf16 v[46:49], v[162:165], v[210:213], v[46:49]
	v_mfma_f32_16x16x32_bf16 v[42:45], v[170:173], v[210:213], v[42:45]
	v_mfma_f32_16x16x32_bf16 v[38:41], v[162:165], v[218:221], v[38:41]
	v_mfma_f32_16x16x32_bf16 v[34:37], v[170:173], v[218:221], v[34:37]
	s_setprio 0
	s_setprio 1
	v_mfma_f32_16x16x32_bf16 v[126:129], v[174:177], v[190:193], v[126:129]
	v_mfma_f32_16x16x32_bf16 v[122:125], v[182:185], v[190:193], v[122:125]
	v_mfma_f32_16x16x32_bf16 v[118:121], v[174:177], v[198:201], v[118:121]
	v_mfma_f32_16x16x32_bf16 v[114:117], v[182:185], v[198:201], v[114:117]
	v_mfma_f32_16x16x32_bf16 v[110:113], v[174:177], v[206:209], v[110:113]
	v_mfma_f32_16x16x32_bf16 v[106:109], v[182:185], v[206:209], v[106:109]
	v_mfma_f32_16x16x32_bf16 v[102:105], v[174:177], v[214:217], v[102:105]
	v_mfma_f32_16x16x32_bf16 v[98:101], v[182:185], v[214:217], v[98:101]
	v_mfma_f32_16x16x32_bf16 v[126:129], v[178:181], v[194:197], v[126:129]
	v_mfma_f32_16x16x32_bf16 v[122:125], v[186:189], v[194:197], v[122:125]
	v_mfma_f32_16x16x32_bf16 v[118:121], v[178:181], v[202:205], v[118:121]
	v_mfma_f32_16x16x32_bf16 v[114:117], v[186:189], v[202:205], v[114:117]
	v_mfma_f32_16x16x32_bf16 v[110:113], v[178:181], v[210:213], v[110:113]
	v_mfma_f32_16x16x32_bf16 v[106:109], v[186:189], v[210:213], v[106:109]
	v_mfma_f32_16x16x32_bf16 v[102:105], v[178:181], v[218:221], v[102:105]
	v_mfma_f32_16x16x32_bf16 v[98:101], v[186:189], v[218:221], v[98:101]
	s_setprio 0
	s_barrier
	s_add_i32 s88, s66, s41
	s_mov_b32 m0, s88
	s_nop 0
	global_load_lds_dwordx4 v138, s[36:37]
	s_add_i32 m0, s88, 0x2000
	s_add_u32 s88, s36, 0x100000
	s_addc_u32 s89, s37, 0
	s_add_i32 vcc_lo, s67, s41
	global_load_lds_dwordx4 v134, s[36:37]
	s_mov_b32 m0, vcc_lo
	s_nop 0
	global_load_lds_dwordx4 v138, s[88:89]
	s_add_i32 m0, vcc_lo, 0x2000
	s_nop 0
	global_load_lds_dwordx4 v134, s[88:89]
	s_mov_b32 m0, s46
	s_nop 0
	global_load_lds_dwordx4 v140, s[38:39]
	s_mov_b32 m0, s47
	s_nop 0
	global_load_lds_dwordx4 v136, s[38:39]
	ds_read_b128 v[190:193], v161 offset:16384
	ds_read_b128 v[194:197], v161 offset:17408
	ds_read_b128 v[198:201], v161 offset:18432
	ds_read_b128 v[202:205], v161 offset:19456
	ds_read_b128 v[206:209], v161 offset:20480
	ds_read_b128 v[210:213], v161 offset:21504
	ds_read_b128 v[214:217], v161 offset:22528
	ds_read_b128 v[218:221], v161 offset:23552
	s_waitcnt vmcnt(8)
	s_waitcnt lgkmcnt(0)
	s_barrier
	s_setprio 1
	s_waitcnt lgkmcnt(0)
	v_mfma_f32_16x16x32_bf16 v[30:33], v[130:133], v[190:193], v[30:33]
	v_mfma_f32_16x16x32_bf16 v[26:29], v[166:169], v[190:193], v[26:29]
	v_mfma_f32_16x16x32_bf16 v[22:25], v[130:133], v[198:201], v[22:25]
	v_mfma_f32_16x16x32_bf16 v[18:21], v[166:169], v[198:201], v[18:21]
	v_mfma_f32_16x16x32_bf16 v[14:17], v[130:133], v[206:209], v[14:17]
	v_mfma_f32_16x16x32_bf16 v[10:13], v[166:169], v[206:209], v[10:13]
	v_mfma_f32_16x16x32_bf16 v[6:9], v[130:133], v[214:217], v[6:9]
	v_mfma_f32_16x16x32_bf16 v[2:5], v[166:169], v[214:217], v[2:5]
	v_mfma_f32_16x16x32_bf16 v[30:33], v[162:165], v[194:197], v[30:33]
	v_mfma_f32_16x16x32_bf16 v[26:29], v[170:173], v[194:197], v[26:29]
	v_mfma_f32_16x16x32_bf16 v[22:25], v[162:165], v[202:205], v[22:25]
	v_mfma_f32_16x16x32_bf16 v[18:21], v[170:173], v[202:205], v[18:21]
	v_mfma_f32_16x16x32_bf16 v[14:17], v[162:165], v[210:213], v[14:17]
	v_mfma_f32_16x16x32_bf16 v[10:13], v[170:173], v[210:213], v[10:13]
	v_mfma_f32_16x16x32_bf16 v[6:9], v[162:165], v[218:221], v[6:9]
	v_mfma_f32_16x16x32_bf16 v[2:5], v[170:173], v[218:221], v[2:5]
	s_setprio 0
	s_setprio 1
	v_mfma_f32_16x16x32_bf16 v[94:97], v[174:177], v[190:193], v[94:97]
	v_mfma_f32_16x16x32_bf16 v[90:93], v[182:185], v[190:193], v[90:93]
	v_mfma_f32_16x16x32_bf16 v[86:89], v[174:177], v[198:201], v[86:89]
	v_mfma_f32_16x16x32_bf16 v[82:85], v[182:185], v[198:201], v[82:85]
	v_mfma_f32_16x16x32_bf16 v[78:81], v[174:177], v[206:209], v[78:81]
	v_mfma_f32_16x16x32_bf16 v[74:77], v[182:185], v[206:209], v[74:77]
	v_mfma_f32_16x16x32_bf16 v[70:73], v[174:177], v[214:217], v[70:73]
	v_mfma_f32_16x16x32_bf16 v[66:69], v[182:185], v[214:217], v[66:69]
	v_mfma_f32_16x16x32_bf16 v[94:97], v[178:181], v[194:197], v[94:97]
	v_mfma_f32_16x16x32_bf16 v[90:93], v[186:189], v[194:197], v[90:93]
	v_mfma_f32_16x16x32_bf16 v[86:89], v[178:181], v[202:205], v[86:89]
	v_mfma_f32_16x16x32_bf16 v[82:85], v[186:189], v[202:205], v[82:85]
	v_mfma_f32_16x16x32_bf16 v[78:81], v[178:181], v[210:213], v[78:81]
	v_mfma_f32_16x16x32_bf16 v[74:77], v[186:189], v[210:213], v[74:77]
	v_mfma_f32_16x16x32_bf16 v[70:73], v[178:181], v[218:221], v[70:73]
	v_mfma_f32_16x16x32_bf16 v[66:69], v[186:189], v[218:221], v[66:69]
	s_setprio 0
	s_barrier
	s_add_i32 s88, 0, 0x18000
	s_add_i32 s89, 0, 0x1c000
	s_add_u32 s38, s38, 0x100000
	s_addc_u32 s39, s39, 0
	s_mov_b32 m0, s58
	s_nop 0
	global_load_lds_dwordx4 v140, s[38:39]
	s_mov_b32 m0, s59
	s_nop 0
	global_load_lds_dwordx4 v136, s[38:39]
	v_add_u32_e32 v154, s88, v157
	ds_read_b128 v[130:133], v154
	ds_read_b128 v[162:165], v154 offset:1024
	ds_read_b128 v[166:169], v154 offset:2048
	ds_read_b128 v[170:173], v154 offset:3072
	v_add_u32_e32 v154, s89, v157
	ds_read_b128 v[174:177], v154
	ds_read_b128 v[178:181], v154 offset:1024
	ds_read_b128 v[182:185], v154 offset:2048
	ds_read_b128 v[186:189], v154 offset:3072
	ds_read_b128 v[190:193], v161 offset:32768
	ds_read_b128 v[194:197], v161 offset:33792
	ds_read_b128 v[198:201], v161 offset:34816
	ds_read_b128 v[202:205], v161 offset:35840
	ds_read_b128 v[206:209], v161 offset:36864
	ds_read_b128 v[210:213], v161 offset:37888
	ds_read_b128 v[214:217], v161 offset:38912
	ds_read_b128 v[218:221], v161 offset:39936
	s_waitcnt vmcnt(8)
	s_waitcnt lgkmcnt(0)
	s_barrier
	s_setprio 1
	s_waitcnt lgkmcnt(0)
	v_mfma_f32_16x16x32_bf16 v[62:65], v[130:133], v[190:193], v[62:65]
	v_mfma_f32_16x16x32_bf16 v[58:61], v[166:169], v[190:193], v[58:61]
	v_mfma_f32_16x16x32_bf16 v[54:57], v[130:133], v[198:201], v[54:57]
	v_mfma_f32_16x16x32_bf16 v[50:53], v[166:169], v[198:201], v[50:53]
	v_mfma_f32_16x16x32_bf16 v[46:49], v[130:133], v[206:209], v[46:49]
	v_mfma_f32_16x16x32_bf16 v[42:45], v[166:169], v[206:209], v[42:45]
	v_mfma_f32_16x16x32_bf16 v[38:41], v[130:133], v[214:217], v[38:41]
	v_mfma_f32_16x16x32_bf16 v[34:37], v[166:169], v[214:217], v[34:37]
	v_mfma_f32_16x16x32_bf16 v[62:65], v[162:165], v[194:197], v[62:65]
	v_mfma_f32_16x16x32_bf16 v[58:61], v[170:173], v[194:197], v[58:61]
	v_mfma_f32_16x16x32_bf16 v[54:57], v[162:165], v[202:205], v[54:57]
	v_mfma_f32_16x16x32_bf16 v[50:53], v[170:173], v[202:205], v[50:53]
	v_mfma_f32_16x16x32_bf16 v[46:49], v[162:165], v[210:213], v[46:49]
	v_mfma_f32_16x16x32_bf16 v[42:45], v[170:173], v[210:213], v[42:45]
	v_mfma_f32_16x16x32_bf16 v[38:41], v[162:165], v[218:221], v[38:41]
	v_mfma_f32_16x16x32_bf16 v[34:37], v[170:173], v[218:221], v[34:37]
	s_setprio 0
	s_setprio 1
	v_mfma_f32_16x16x32_bf16 v[126:129], v[174:177], v[190:193], v[126:129]
	v_mfma_f32_16x16x32_bf16 v[122:125], v[182:185], v[190:193], v[122:125]
	v_mfma_f32_16x16x32_bf16 v[118:121], v[174:177], v[198:201], v[118:121]
	v_mfma_f32_16x16x32_bf16 v[114:117], v[182:185], v[198:201], v[114:117]
	v_mfma_f32_16x16x32_bf16 v[110:113], v[174:177], v[206:209], v[110:113]
	v_mfma_f32_16x16x32_bf16 v[106:109], v[182:185], v[206:209], v[106:109]
	v_mfma_f32_16x16x32_bf16 v[102:105], v[174:177], v[214:217], v[102:105]
	v_mfma_f32_16x16x32_bf16 v[98:101], v[182:185], v[214:217], v[98:101]
	v_mfma_f32_16x16x32_bf16 v[126:129], v[178:181], v[194:197], v[126:129]
	v_mfma_f32_16x16x32_bf16 v[122:125], v[186:189], v[194:197], v[122:125]
	v_mfma_f32_16x16x32_bf16 v[118:121], v[178:181], v[202:205], v[118:121]
	v_mfma_f32_16x16x32_bf16 v[114:117], v[186:189], v[202:205], v[114:117]
	v_mfma_f32_16x16x32_bf16 v[110:113], v[178:181], v[210:213], v[110:113]
	v_mfma_f32_16x16x32_bf16 v[106:109], v[186:189], v[210:213], v[106:109]
	v_mfma_f32_16x16x32_bf16 v[102:105], v[178:181], v[218:221], v[102:105]
	v_mfma_f32_16x16x32_bf16 v[98:101], v[186:189], v[218:221], v[98:101]
	s_setprio 0
	s_barrier
	s_add_u32 s38, s36, 0x4000
	s_addc_u32 s39, s37, 0
	s_add_i32 s88, s88, s41
	s_mov_b32 m0, s88
	s_nop 0
	global_load_lds_dwordx4 v138, s[38:39]
	s_add_i32 m0, s88, 0x2000
	s_add_u32 s36, s36, 0x104000
	s_addc_u32 s37, s37, 0
	global_load_lds_dwordx4 v134, s[38:39]
	s_add_i32 s38, s89, s41
	s_mov_b32 m0, s38
	s_nop 0
	global_load_lds_dwordx4 v138, s[36:37]
	s_add_i32 m0, s38, 0x2000
	s_nop 0
	global_load_lds_dwordx4 v134, s[36:37]
	s_mov_b32 m0, s64
	s_nop 0
	global_load_lds_dwordx4 v140, s[34:35]
	s_mov_b32 m0, s65
	s_nop 0
	global_load_lds_dwordx4 v136, s[34:35]
	ds_read_b128 v[190:193], v161 offset:49152
	ds_read_b128 v[194:197], v161 offset:50176
	ds_read_b128 v[198:201], v161 offset:51200
	ds_read_b128 v[202:205], v161 offset:52224
	ds_read_b128 v[206:209], v161 offset:53248
	ds_read_b128 v[210:213], v161 offset:54272
	ds_read_b128 v[214:217], v161 offset:55296
	ds_read_b128 v[218:221], v161 offset:56320
	s_waitcnt vmcnt(8)
	s_waitcnt lgkmcnt(0)
	s_barrier
	s_setprio 1
	s_waitcnt lgkmcnt(0)
	v_mfma_f32_16x16x32_bf16 v[30:33], v[130:133], v[190:193], v[30:33]
	v_mfma_f32_16x16x32_bf16 v[26:29], v[166:169], v[190:193], v[26:29]
	v_mfma_f32_16x16x32_bf16 v[22:25], v[130:133], v[198:201], v[22:25]
	v_mfma_f32_16x16x32_bf16 v[18:21], v[166:169], v[198:201], v[18:21]
	v_mfma_f32_16x16x32_bf16 v[14:17], v[130:133], v[206:209], v[14:17]
	v_mfma_f32_16x16x32_bf16 v[10:13], v[166:169], v[206:209], v[10:13]
	v_mfma_f32_16x16x32_bf16 v[6:9], v[130:133], v[214:217], v[6:9]
	v_mfma_f32_16x16x32_bf16 v[2:5], v[166:169], v[214:217], v[2:5]
	v_mfma_f32_16x16x32_bf16 v[30:33], v[162:165], v[194:197], v[30:33]
	v_mfma_f32_16x16x32_bf16 v[26:29], v[170:173], v[194:197], v[26:29]
	v_mfma_f32_16x16x32_bf16 v[22:25], v[162:165], v[202:205], v[22:25]
	v_mfma_f32_16x16x32_bf16 v[18:21], v[170:173], v[202:205], v[18:21]
	v_mfma_f32_16x16x32_bf16 v[14:17], v[162:165], v[210:213], v[14:17]
	v_mfma_f32_16x16x32_bf16 v[10:13], v[170:173], v[210:213], v[10:13]
	v_mfma_f32_16x16x32_bf16 v[6:9], v[162:165], v[218:221], v[6:9]
	v_mfma_f32_16x16x32_bf16 v[2:5], v[170:173], v[218:221], v[2:5]
	s_setprio 0
	s_setprio 1
	v_mfma_f32_16x16x32_bf16 v[94:97], v[174:177], v[190:193], v[94:97]
	v_mfma_f32_16x16x32_bf16 v[90:93], v[182:185], v[190:193], v[90:93]
	v_mfma_f32_16x16x32_bf16 v[86:89], v[174:177], v[198:201], v[86:89]
	v_mfma_f32_16x16x32_bf16 v[82:85], v[182:185], v[198:201], v[82:85]
	v_mfma_f32_16x16x32_bf16 v[78:81], v[174:177], v[206:209], v[78:81]
	v_mfma_f32_16x16x32_bf16 v[74:77], v[182:185], v[206:209], v[74:77]
	v_mfma_f32_16x16x32_bf16 v[70:73], v[174:177], v[214:217], v[70:73]
	v_mfma_f32_16x16x32_bf16 v[66:69], v[182:185], v[214:217], v[66:69]
	v_mfma_f32_16x16x32_bf16 v[94:97], v[178:181], v[194:197], v[94:97]
	v_mfma_f32_16x16x32_bf16 v[90:93], v[186:189], v[194:197], v[90:93]
	v_mfma_f32_16x16x32_bf16 v[86:89], v[178:181], v[202:205], v[86:89]
	v_mfma_f32_16x16x32_bf16 v[82:85], v[186:189], v[202:205], v[82:85]
	v_mfma_f32_16x16x32_bf16 v[78:81], v[178:181], v[210:213], v[78:81]
	v_mfma_f32_16x16x32_bf16 v[74:77], v[186:189], v[210:213], v[74:77]
	v_mfma_f32_16x16x32_bf16 v[70:73], v[178:181], v[218:221], v[70:73]
	v_mfma_f32_16x16x32_bf16 v[66:69], v[186:189], v[218:221], v[66:69]
	s_setprio 0
	s_barrier
	s_add_i32 s87, s87, 2
	s_add_u32 s26, s26, 0x8000
	s_addc_u32 s27, s27, 0
	s_add_u32 s83, s83, 0x8000
	s_addc_u32 s86, s86, 0
	s_cmp_gt_u32 s87, 61
	s_cbranch_scc0 .LBB0_376
	s_and_b64 vcc, exec, s[14:15]
	s_cbranch_vccz .LBB0_379
	s_barrier

.LBB0_536:
	s_add_u32 s30, s26, 0xfff04000
	s_addc_u32 s31, s27, -1
	s_cmp_eq_u32 s80, 60
	s_cselect_b32 s36, s74, s30
	s_cselect_b32 s37, s21, s31
	s_cselect_b32 s34, s75, s78
	s_cselect_b32 s35, s19, s79
	s_add_u32 s30, s36, 0x4000
	s_addc_u32 s31, s37, 0
	s_add_i32 m0, s42, 0xc000
	s_nop 0
	global_load_lds_dwordx4 v146, s[26:27]
	s_add_i32 m0, s42, 0xe000
	s_nop 0
	global_load_lds_dwordx4 v148, s[26:27]
	ds_read_b128 v[130:133], v159
	ds_read_b128 v[162:165], v159 offset:1024
	ds_read_b128 v[166:169], v159 offset:2048
	ds_read_b128 v[170:173], v159 offset:3072
	ds_read_b128 v[174:177], v160
	ds_read_b128 v[178:181], v160 offset:1024
	ds_read_b128 v[182:185], v160 offset:2048
	ds_read_b128 v[186:189], v160 offset:3072
	ds_read_b128 v[190:193], v161
	ds_read_b128 v[194:197], v161 offset:1024
	ds_read_b128 v[198:201], v161 offset:2048
	ds_read_b128 v[202:205], v161 offset:3072
	ds_read_b128 v[206:209], v161 offset:4096
	ds_read_b128 v[210:213], v161 offset:5120
	ds_read_b128 v[214:217], v161 offset:6144
	ds_read_b128 v[218:221], v161 offset:7168
	s_waitcnt vmcnt(8)
	s_waitcnt lgkmcnt(0)
	s_barrier
	s_setprio 1
	s_waitcnt lgkmcnt(0)
	v_mfma_f32_16x16x32_bf16 v[62:65], v[130:133], v[190:193], v[62:65]
	v_mfma_f32_16x16x32_bf16 v[58:61], v[166:169], v[190:193], v[58:61]
	v_mfma_f32_16x16x32_bf16 v[54:57], v[130:133], v[198:201], v[54:57]
	v_mfma_f32_16x16x32_bf16 v[50:53], v[166:169], v[198:201], v[50:53]
	v_mfma_f32_16x16x32_bf16 v[46:49], v[130:133], v[206:209], v[46:49]
	v_mfma_f32_16x16x32_bf16 v[42:45], v[166:169], v[206:209], v[42:45]
	v_mfma_f32_16x16x32_bf16 v[38:41], v[130:133], v[214:217], v[38:41]
	v_mfma_f32_16x16x32_bf16 v[34:37], v[166:169], v[214:217], v[34:37]
	v_mfma_f32_16x16x32_bf16 v[62:65], v[162:165], v[194:197], v[62:65]
	v_mfma_f32_16x16x32_bf16 v[58:61], v[170:173], v[194:197], v[58:61]
	v_mfma_f32_16x16x32_bf16 v[54:57], v[162:165], v[202:205], v[54:57]
	v_mfma_f32_16x16x32_bf16 v[50:53], v[170:173], v[202:205], v[50:53]
	v_mfma_f32_16x16x32_bf16 v[46:49], v[162:165], v[210:213], v[46:49]
	v_mfma_f32_16x16x32_bf16 v[42:45], v[170:173], v[210:213], v[42:45]
	v_mfma_f32_16x16x32_bf16 v[38:41], v[162:165], v[218:221], v[38:41]
	v_mfma_f32_16x16x32_bf16 v[34:37], v[170:173], v[218:221], v[34:37]
	s_setprio 0
	s_setprio 1
	v_mfma_f32_16x16x32_bf16 v[126:129], v[174:177], v[190:193], v[126:129]
	v_mfma_f32_16x16x32_bf16 v[122:125], v[182:185], v[190:193], v[122:125]
	v_mfma_f32_16x16x32_bf16 v[118:121], v[174:177], v[198:201], v[118:121]
	v_mfma_f32_16x16x32_bf16 v[114:117], v[182:185], v[198:201], v[114:117]
	v_mfma_f32_16x16x32_bf16 v[110:113], v[174:177], v[206:209], v[110:113]
	v_mfma_f32_16x16x32_bf16 v[106:109], v[182:185], v[206:209], v[106:109]
	v_mfma_f32_16x16x32_bf16 v[102:105], v[174:177], v[214:217], v[102:105]
	v_mfma_f32_16x16x32_bf16 v[98:101], v[182:185], v[214:217], v[98:101]
	v_mfma_f32_16x16x32_bf16 v[126:129], v[178:181], v[194:197], v[126:129]
	v_mfma_f32_16x16x32_bf16 v[122:125], v[186:189], v[194:197], v[122:125]
	v_mfma_f32_16x16x32_bf16 v[118:121], v[178:181], v[202:205], v[118:121]
	v_mfma_f32_16x16x32_bf16 v[114:117], v[186:189], v[202:205], v[114:117]
	v_mfma_f32_16x16x32_bf16 v[110:113], v[178:181], v[210:213], v[110:113]
	v_mfma_f32_16x16x32_bf16 v[106:109], v[186:189], v[210:213], v[106:109]
	v_mfma_f32_16x16x32_bf16 v[102:105], v[178:181], v[218:221], v[102:105]
	v_mfma_f32_16x16x32_bf16 v[98:101], v[186:189], v[218:221], v[98:101]
	s_setprio 0
	s_barrier
	s_add_i32 s81, s62, s38
	s_mov_b32 m0, s81
	s_nop 0
	global_load_lds_dwordx4 v138, s[34:35]
	s_add_i32 m0, s81, 0x2000
	s_add_u32 s86, s34, 0x100000
	s_addc_u32 s87, s35, 0
	s_add_i32 s81, s63, s38
	global_load_lds_dwordx4 v134, s[34:35]
	s_mov_b32 m0, s81
	s_nop 0
	global_load_lds_dwordx4 v138, s[86:87]
	s_add_i32 m0, s81, 0x2000
	s_nop 0
	global_load_lds_dwordx4 v134, s[86:87]
	s_mov_b32 m0, s42
	s_nop 0
	global_load_lds_dwordx4 v140, s[36:37]
	s_mov_b32 m0, s43
	s_nop 0
	global_load_lds_dwordx4 v136, s[36:37]
	ds_read_b128 v[190:193], v161 offset:16384
	ds_read_b128 v[194:197], v161 offset:17408
	ds_read_b128 v[198:201], v161 offset:18432
	ds_read_b128 v[202:205], v161 offset:19456
	ds_read_b128 v[206:209], v161 offset:20480
	ds_read_b128 v[210:213], v161 offset:21504
	ds_read_b128 v[214:217], v161 offset:22528
	ds_read_b128 v[218:221], v161 offset:23552
	s_waitcnt vmcnt(8)
	s_waitcnt lgkmcnt(0)
	s_barrier
	s_setprio 1
	s_waitcnt lgkmcnt(0)
	v_mfma_f32_16x16x32_bf16 v[30:33], v[130:133], v[190:193], v[30:33]
	v_mfma_f32_16x16x32_bf16 v[26:29], v[166:169], v[190:193], v[26:29]
	v_mfma_f32_16x16x32_bf16 v[22:25], v[130:133], v[198:201], v[22:25]
	v_mfma_f32_16x16x32_bf16 v[18:21], v[166:169], v[198:201], v[18:21]
	v_mfma_f32_16x16x32_bf16 v[14:17], v[130:133], v[206:209], v[14:17]
	v_mfma_f32_16x16x32_bf16 v[10:13], v[166:169], v[206:209], v[10:13]
	v_mfma_f32_16x16x32_bf16 v[6:9], v[130:133], v[214:217], v[6:9]
	v_mfma_f32_16x16x32_bf16 v[2:5], v[166:169], v[214:217], v[2:5]
	v_mfma_f32_16x16x32_bf16 v[30:33], v[162:165], v[194:197], v[30:33]
	v_mfma_f32_16x16x32_bf16 v[26:29], v[170:173], v[194:197], v[26:29]
	v_mfma_f32_16x16x32_bf16 v[22:25], v[162:165], v[202:205], v[22:25]
	v_mfma_f32_16x16x32_bf16 v[18:21], v[170:173], v[202:205], v[18:21]
	v_mfma_f32_16x16x32_bf16 v[14:17], v[162:165], v[210:213], v[14:17]
	v_mfma_f32_16x16x32_bf16 v[10:13], v[170:173], v[210:213], v[10:13]
	v_mfma_f32_16x16x32_bf16 v[6:9], v[162:165], v[218:221], v[6:9]
	v_mfma_f32_16x16x32_bf16 v[2:5], v[170:173], v[218:221], v[2:5]
	s_setprio 0
	s_setprio 1
	v_mfma_f32_16x16x32_bf16 v[94:97], v[174:177], v[190:193], v[94:97]
	v_mfma_f32_16x16x32_bf16 v[90:93], v[182:185], v[190:193], v[90:93]
	v_mfma_f32_16x16x32_bf16 v[86:89], v[174:177], v[198:201], v[86:89]
	v_mfma_f32_16x16x32_bf16 v[82:85], v[182:185], v[198:201], v[82:85]
	v_mfma_f32_16x16x32_bf16 v[78:81], v[174:177], v[206:209], v[78:81]
	v_mfma_f32_16x16x32_bf16 v[74:77], v[182:185], v[206:209], v[74:77]
	v_mfma_f32_16x16x32_bf16 v[70:73], v[174:177], v[214:217], v[70:73]
	v_mfma_f32_16x16x32_bf16 v[66:69], v[182:185], v[214:217], v[66:69]
	v_mfma_f32_16x16x32_bf16 v[94:97], v[178:181], v[194:197], v[94:97]
	v_mfma_f32_16x16x32_bf16 v[90:93], v[186:189], v[194:197], v[90:93]
	v_mfma_f32_16x16x32_bf16 v[86:89], v[178:181], v[202:205], v[86:89]
	v_mfma_f32_16x16x32_bf16 v[82:85], v[186:189], v[202:205], v[82:85]
	v_mfma_f32_16x16x32_bf16 v[78:81], v[178:181], v[210:213], v[78:81]
	v_mfma_f32_16x16x32_bf16 v[74:77], v[186:189], v[210:213], v[74:77]
	v_mfma_f32_16x16x32_bf16 v[70:73], v[178:181], v[218:221], v[70:73]
	v_mfma_f32_16x16x32_bf16 v[66:69], v[186:189], v[218:221], v[66:69]
	s_setprio 0
	s_barrier
	s_add_i32 s81, 0, 0x18000
	s_add_i32 s83, 0, 0x1c000
	s_add_u32 s36, s36, 0x100000
	s_addc_u32 s37, s37, 0
	s_mov_b32 m0, s46
	s_nop 0
	global_load_lds_dwordx4 v140, s[36:37]
	s_mov_b32 m0, s47
	s_nop 0
	global_load_lds_dwordx4 v136, s[36:37]
	v_add_u32_e32 v154, s81, v157
	ds_read_b128 v[130:133], v154
	ds_read_b128 v[162:165], v154 offset:1024
	ds_read_b128 v[166:169], v154 offset:2048
	ds_read_b128 v[170:173], v154 offset:3072
	v_add_u32_e32 v154, s83, v157
	ds_read_b128 v[174:177], v154
	ds_read_b128 v[178:181], v154 offset:1024
	ds_read_b128 v[182:185], v154 offset:2048
	ds_read_b128 v[186:189], v154 offset:3072
	ds_read_b128 v[190:193], v161 offset:32768
	ds_read_b128 v[194:197], v161 offset:33792
	ds_read_b128 v[198:201], v161 offset:34816
	ds_read_b128 v[202:205], v161 offset:35840
	ds_read_b128 v[206:209], v161 offset:36864
	ds_read_b128 v[210:213], v161 offset:37888
	ds_read_b128 v[214:217], v161 offset:38912
	ds_read_b128 v[218:221], v161 offset:39936
	s_waitcnt vmcnt(8)
	s_waitcnt lgkmcnt(0)
	s_barrier
	s_setprio 1
	s_waitcnt lgkmcnt(0)
	v_mfma_f32_16x16x32_bf16 v[62:65], v[130:133], v[190:193], v[62:65]
	v_mfma_f32_16x16x32_bf16 v[58:61], v[166:169], v[190:193], v[58:61]
	v_mfma_f32_16x16x32_bf16 v[54:57], v[130:133], v[198:201], v[54:57]
	v_mfma_f32_16x16x32_bf16 v[50:53], v[166:169], v[198:201], v[50:53]
	v_mfma_f32_16x16x32_bf16 v[46:49], v[130:133], v[206:209], v[46:49]
	v_mfma_f32_16x16x32_bf16 v[42:45], v[166:169], v[206:209], v[42:45]
	v_mfma_f32_16x16x32_bf16 v[38:41], v[130:133], v[214:217], v[38:41]
	v_mfma_f32_16x16x32_bf16 v[34:37], v[166:169], v[214:217], v[34:37]
	v_mfma_f32_16x16x32_bf16 v[62:65], v[162:165], v[194:197], v[62:65]
	v_mfma_f32_16x16x32_bf16 v[58:61], v[170:173], v[194:197], v[58:61]
	v_mfma_f32_16x16x32_bf16 v[54:57], v[162:165], v[202:205], v[54:57]
	v_mfma_f32_16x16x32_bf16 v[50:53], v[170:173], v[202:205], v[50:53]
	v_mfma_f32_16x16x32_bf16 v[46:49], v[162:165], v[210:213], v[46:49]
	v_mfma_f32_16x16x32_bf16 v[42:45], v[170:173], v[210:213], v[42:45]
	v_mfma_f32_16x16x32_bf16 v[38:41], v[162:165], v[218:221], v[38:41]
	v_mfma_f32_16x16x32_bf16 v[34:37], v[170:173], v[218:221], v[34:37]
	s_setprio 0
	s_setprio 1
	v_mfma_f32_16x16x32_bf16 v[126:129], v[174:177], v[190:193], v[126:129]
	v_mfma_f32_16x16x32_bf16 v[122:125], v[182:185], v[190:193], v[122:125]
	v_mfma_f32_16x16x32_bf16 v[118:121], v[174:177], v[198:201], v[118:121]
	v_mfma_f32_16x16x32_bf16 v[114:117], v[182:185], v[198:201], v[114:117]
	v_mfma_f32_16x16x32_bf16 v[110:113], v[174:177], v[206:209], v[110:113]
	v_mfma_f32_16x16x32_bf16 v[106:109], v[182:185], v[206:209], v[106:109]
	v_mfma_f32_16x16x32_bf16 v[102:105], v[174:177], v[214:217], v[102:105]
	v_mfma_f32_16x16x32_bf16 v[98:101], v[182:185], v[214:217], v[98:101]
	v_mfma_f32_16x16x32_bf16 v[126:129], v[178:181], v[194:197], v[126:129]
	v_mfma_f32_16x16x32_bf16 v[122:125], v[186:189], v[194:197], v[122:125]
	v_mfma_f32_16x16x32_bf16 v[118:121], v[178:181], v[202:205], v[118:121]
	v_mfma_f32_16x16x32_bf16 v[114:117], v[186:189], v[202:205], v[114:117]
	v_mfma_f32_16x16x32_bf16 v[110:113], v[178:181], v[210:213], v[110:113]
	v_mfma_f32_16x16x32_bf16 v[106:109], v[186:189], v[210:213], v[106:109]
	v_mfma_f32_16x16x32_bf16 v[102:105], v[178:181], v[218:221], v[102:105]
	v_mfma_f32_16x16x32_bf16 v[98:101], v[186:189], v[218:221], v[98:101]
	s_setprio 0
	s_barrier
	s_add_u32 s36, s34, 0x4000
	s_addc_u32 s37, s35, 0
	s_add_i32 s81, s81, s38
	s_mov_b32 m0, s81
	s_nop 0
	global_load_lds_dwordx4 v138, s[36:37]
	s_add_i32 m0, s81, 0x2000
	s_add_u32 s34, s34, 0x104000
	s_addc_u32 s35, s35, 0
	global_load_lds_dwordx4 v134, s[36:37]
	s_add_i32 s36, s83, s38
	s_mov_b32 m0, s36
	s_nop 0
	global_load_lds_dwordx4 v138, s[34:35]
	s_add_i32 m0, s36, 0x2000
	s_nop 0
	global_load_lds_dwordx4 v134, s[34:35]
	s_mov_b32 m0, s58
	s_nop 0
	global_load_lds_dwordx4 v140, s[30:31]
	s_mov_b32 m0, s59
	s_nop 0
	global_load_lds_dwordx4 v136, s[30:31]
	ds_read_b128 v[190:193], v161 offset:49152
	ds_read_b128 v[194:197], v161 offset:50176
	ds_read_b128 v[198:201], v161 offset:51200
	ds_read_b128 v[202:205], v161 offset:52224
	ds_read_b128 v[206:209], v161 offset:53248
	ds_read_b128 v[210:213], v161 offset:54272
	ds_read_b128 v[214:217], v161 offset:55296
	ds_read_b128 v[218:221], v161 offset:56320
	s_waitcnt vmcnt(8)
	s_waitcnt lgkmcnt(0)
	s_barrier
	s_setprio 1
	s_waitcnt lgkmcnt(0)
	v_mfma_f32_16x16x32_bf16 v[30:33], v[130:133], v[190:193], v[30:33]
	v_mfma_f32_16x16x32_bf16 v[26:29], v[166:169], v[190:193], v[26:29]
	v_mfma_f32_16x16x32_bf16 v[22:25], v[130:133], v[198:201], v[22:25]
	v_mfma_f32_16x16x32_bf16 v[18:21], v[166:169], v[198:201], v[18:21]
	v_mfma_f32_16x16x32_bf16 v[14:17], v[130:133], v[206:209], v[14:17]
	v_mfma_f32_16x16x32_bf16 v[10:13], v[166:169], v[206:209], v[10:13]
	v_mfma_f32_16x16x32_bf16 v[6:9], v[130:133], v[214:217], v[6:9]
	v_mfma_f32_16x16x32_bf16 v[2:5], v[166:169], v[214:217], v[2:5]
	v_mfma_f32_16x16x32_bf16 v[30:33], v[162:165], v[194:197], v[30:33]
	v_mfma_f32_16x16x32_bf16 v[26:29], v[170:173], v[194:197], v[26:29]
	v_mfma_f32_16x16x32_bf16 v[22:25], v[162:165], v[202:205], v[22:25]
	v_mfma_f32_16x16x32_bf16 v[18:21], v[170:173], v[202:205], v[18:21]
	v_mfma_f32_16x16x32_bf16 v[14:17], v[162:165], v[210:213], v[14:17]
	v_mfma_f32_16x16x32_bf16 v[10:13], v[170:173], v[210:213], v[10:13]
	v_mfma_f32_16x16x32_bf16 v[6:9], v[162:165], v[218:221], v[6:9]
	v_mfma_f32_16x16x32_bf16 v[2:5], v[170:173], v[218:221], v[2:5]
	s_setprio 0
	s_setprio 1
	v_mfma_f32_16x16x32_bf16 v[94:97], v[174:177], v[190:193], v[94:97]
	v_mfma_f32_16x16x32_bf16 v[90:93], v[182:185], v[190:193], v[90:93]
	v_mfma_f32_16x16x32_bf16 v[86:89], v[174:177], v[198:201], v[86:89]
	v_mfma_f32_16x16x32_bf16 v[82:85], v[182:185], v[198:201], v[82:85]
	v_mfma_f32_16x16x32_bf16 v[78:81], v[174:177], v[206:209], v[78:81]
	v_mfma_f32_16x16x32_bf16 v[74:77], v[182:185], v[206:209], v[74:77]
	v_mfma_f32_16x16x32_bf16 v[70:73], v[174:177], v[214:217], v[70:73]
	v_mfma_f32_16x16x32_bf16 v[66:69], v[182:185], v[214:217], v[66:69]
	v_mfma_f32_16x16x32_bf16 v[94:97], v[178:181], v[194:197], v[94:97]
	v_mfma_f32_16x16x32_bf16 v[90:93], v[186:189], v[194:197], v[90:93]
	v_mfma_f32_16x16x32_bf16 v[86:89], v[178:181], v[202:205], v[86:89]
	v_mfma_f32_16x16x32_bf16 v[82:85], v[186:189], v[202:205], v[82:85]
	v_mfma_f32_16x16x32_bf16 v[78:81], v[178:181], v[210:213], v[78:81]
	v_mfma_f32_16x16x32_bf16 v[74:77], v[186:189], v[210:213], v[74:77]
	v_mfma_f32_16x16x32_bf16 v[70:73], v[178:181], v[218:221], v[70:73]
	v_mfma_f32_16x16x32_bf16 v[66:69], v[186:189], v[218:221], v[66:69]
	s_setprio 0
	s_barrier
	s_add_i32 s80, s80, 2
	s_add_u32 s26, s26, 0x8000
	s_addc_u32 s27, s27, 0
	s_add_u32 s78, s78, 0x8000
	s_addc_u32 s79, s79, 0
	s_cmp_gt_u32 s80, 61
	s_cbranch_scc0 .LBB0_536
	s_and_b64 vcc, exec, s[14:15]
	s_cbranch_vccz .LBB0_539
	s_barrier

.LBB0_1005:
	s_add_i32 s70, s31, 2
	s_add_u32 s26, s24, 0xfff44000
	s_addc_u32 s27, s25, -1
	s_cmp_eq_u32 s67, s31
	s_cselect_b32 s34, s6, s26
	s_cselect_b32 s35, s7, s27
	s_cselect_b32 s30, s20, s68
	s_cselect_b32 s31, s21, s69
	s_add_u32 s26, s34, 0x4000
	s_addc_u32 s27, s35, 0
	s_add_i32 m0, s37, 0xc000
	s_nop 0
	global_load_lds_dwordx4 v190, s[24:25]
	s_add_i32 m0, s37, 0xe000
	s_nop 0
	global_load_lds_dwordx4 v192, s[24:25]
	v_add_u32_e32 v142, s46, v200
	v_add_u32_e32 v158, s47, v200
	ds_read_b128 v[130:133], v142
	ds_read_b128 v[134:137], v142 offset:1024
	ds_read_b128 v[138:141], v142 offset:2048
	ds_read_b128 v[142:145], v142 offset:3072
	ds_read_b128 v[146:149], v158
	ds_read_b128 v[150:153], v158 offset:1024
	ds_read_b128 v[154:157], v158 offset:2048
	ds_read_b128 v[158:161], v158 offset:3072
	ds_read_b128 v[162:165], v201
	ds_read_b128 v[166:169], v201 offset:1024
	ds_read_b128 v[170:173], v201 offset:2048
	ds_read_b128 v[174:177], v201 offset:3072
	ds_read_b128 v[202:205], v201 offset:4096
	ds_read_b128 v[206:209], v201 offset:5120
	ds_read_b128 v[210:213], v201 offset:6144
	ds_read_b128 v[214:217], v201 offset:7168
	s_waitcnt vmcnt(8)
	s_waitcnt lgkmcnt(0)
	s_barrier
	s_setprio 1
	s_waitcnt lgkmcnt(0)
	v_mfma_f32_16x16x32_bf16 v[126:129], v[130:133], v[162:165], v[126:129]
	v_mfma_f32_16x16x32_bf16 v[122:125], v[138:141], v[162:165], v[122:125]
	v_mfma_f32_16x16x32_bf16 v[118:121], v[130:133], v[170:173], v[118:121]
	v_mfma_f32_16x16x32_bf16 v[114:117], v[138:141], v[170:173], v[114:117]
	v_mfma_f32_16x16x32_bf16 v[110:113], v[130:133], v[202:205], v[110:113]
	v_mfma_f32_16x16x32_bf16 v[106:109], v[138:141], v[202:205], v[106:109]
	v_mfma_f32_16x16x32_bf16 v[102:105], v[130:133], v[210:213], v[102:105]
	v_mfma_f32_16x16x32_bf16 v[98:101], v[138:141], v[210:213], v[98:101]
	v_mfma_f32_16x16x32_bf16 v[126:129], v[134:137], v[166:169], v[126:129]
	v_mfma_f32_16x16x32_bf16 v[122:125], v[142:145], v[166:169], v[122:125]
	v_mfma_f32_16x16x32_bf16 v[118:121], v[134:137], v[174:177], v[118:121]
	v_mfma_f32_16x16x32_bf16 v[114:117], v[142:145], v[174:177], v[114:117]
	v_mfma_f32_16x16x32_bf16 v[110:113], v[134:137], v[206:209], v[110:113]
	v_mfma_f32_16x16x32_bf16 v[106:109], v[142:145], v[206:209], v[106:109]
	v_mfma_f32_16x16x32_bf16 v[102:105], v[134:137], v[214:217], v[102:105]
	v_mfma_f32_16x16x32_bf16 v[98:101], v[142:145], v[214:217], v[98:101]
	s_setprio 0
	s_setprio 1
	v_mfma_f32_16x16x32_bf16 v[94:97], v[146:149], v[162:165], v[94:97]
	v_mfma_f32_16x16x32_bf16 v[90:93], v[154:157], v[162:165], v[90:93]
	v_mfma_f32_16x16x32_bf16 v[86:89], v[146:149], v[170:173], v[86:89]
	v_mfma_f32_16x16x32_bf16 v[82:85], v[154:157], v[170:173], v[82:85]
	v_mfma_f32_16x16x32_bf16 v[78:81], v[146:149], v[202:205], v[78:81]
	v_mfma_f32_16x16x32_bf16 v[74:77], v[154:157], v[202:205], v[74:77]
	v_mfma_f32_16x16x32_bf16 v[66:69], v[146:149], v[210:213], v[66:69]
	v_mfma_f32_16x16x32_bf16 v[58:61], v[154:157], v[210:213], v[58:61]
	v_mfma_f32_16x16x32_bf16 v[94:97], v[150:153], v[166:169], v[94:97]
	v_mfma_f32_16x16x32_bf16 v[90:93], v[158:161], v[166:169], v[90:93]
	v_mfma_f32_16x16x32_bf16 v[86:89], v[150:153], v[174:177], v[86:89]
	v_mfma_f32_16x16x32_bf16 v[82:85], v[158:161], v[174:177], v[82:85]
	v_mfma_f32_16x16x32_bf16 v[78:81], v[150:153], v[206:209], v[78:81]
	v_mfma_f32_16x16x32_bf16 v[74:77], v[158:161], v[206:209], v[74:77]
	v_mfma_f32_16x16x32_bf16 v[66:69], v[150:153], v[214:217], v[66:69]
	v_mfma_f32_16x16x32_bf16 v[58:61], v[158:161], v[214:217], v[58:61]
	s_setprio 0
	s_barrier
	s_add_i32 s71, s46, s36
	s_mov_b32 m0, s71
	s_nop 0
	global_load_lds_dwordx4 v182, s[30:31]
	s_add_i32 m0, s71, 0x2000
	s_add_u32 s72, s30, 0xc0000
	s_addc_u32 s73, s31, 0
	s_add_i32 s71, s47, s36
	global_load_lds_dwordx4 v178, s[30:31]
	s_mov_b32 m0, s71
	s_nop 0
	global_load_lds_dwordx4 v182, s[72:73]
	s_add_i32 m0, s71, 0x2000
	s_nop 0
	global_load_lds_dwordx4 v178, s[72:73]
	s_mov_b32 m0, s37
	s_nop 0
	global_load_lds_dwordx4 v184, s[34:35]
	s_mov_b32 m0, s38
	s_nop 0
	global_load_lds_dwordx4 v180, s[34:35]
	ds_read_b128 v[162:165], v201 offset:16384
	ds_read_b128 v[166:169], v201 offset:17408
	ds_read_b128 v[170:173], v201 offset:18432
	ds_read_b128 v[174:177], v201 offset:19456
	ds_read_b128 v[202:205], v201 offset:20480
	ds_read_b128 v[206:209], v201 offset:21504
	ds_read_b128 v[210:213], v201 offset:22528
	ds_read_b128 v[214:217], v201 offset:23552
	s_waitcnt vmcnt(8)
	s_waitcnt lgkmcnt(0)
	s_barrier
	s_setprio 1
	s_waitcnt lgkmcnt(0)
	v_mfma_f32_16x16x32_bf16 v[70:73], v[130:133], v[162:165], v[70:73]
	v_mfma_f32_16x16x32_bf16 v[62:65], v[138:141], v[162:165], v[62:65]
	v_mfma_f32_16x16x32_bf16 v[54:57], v[130:133], v[170:173], v[54:57]
	v_mfma_f32_16x16x32_bf16 v[50:53], v[138:141], v[170:173], v[50:53]
	v_mfma_f32_16x16x32_bf16 v[46:49], v[130:133], v[202:205], v[46:49]
	v_mfma_f32_16x16x32_bf16 v[42:45], v[138:141], v[202:205], v[42:45]
	v_mfma_f32_16x16x32_bf16 v[38:41], v[130:133], v[210:213], v[38:41]
	v_mfma_f32_16x16x32_bf16 v[34:37], v[138:141], v[210:213], v[34:37]
	v_mfma_f32_16x16x32_bf16 v[70:73], v[134:137], v[166:169], v[70:73]
	v_mfma_f32_16x16x32_bf16 v[62:65], v[142:145], v[166:169], v[62:65]
	v_mfma_f32_16x16x32_bf16 v[54:57], v[134:137], v[174:177], v[54:57]
	v_mfma_f32_16x16x32_bf16 v[50:53], v[142:145], v[174:177], v[50:53]
	v_mfma_f32_16x16x32_bf16 v[46:49], v[134:137], v[206:209], v[46:49]
	v_mfma_f32_16x16x32_bf16 v[42:45], v[142:145], v[206:209], v[42:45]
	v_mfma_f32_16x16x32_bf16 v[38:41], v[134:137], v[214:217], v[38:41]
	v_mfma_f32_16x16x32_bf16 v[34:37], v[142:145], v[214:217], v[34:37]
	s_setprio 0
	s_setprio 1
	v_mfma_f32_16x16x32_bf16 v[30:33], v[146:149], v[162:165], v[30:33]
	v_mfma_f32_16x16x32_bf16 v[26:29], v[154:157], v[162:165], v[26:29]
	v_mfma_f32_16x16x32_bf16 v[22:25], v[146:149], v[170:173], v[22:25]
	v_mfma_f32_16x16x32_bf16 v[18:21], v[154:157], v[170:173], v[18:21]
	v_mfma_f32_16x16x32_bf16 v[14:17], v[146:149], v[202:205], v[14:17]
	v_mfma_f32_16x16x32_bf16 v[10:13], v[154:157], v[202:205], v[10:13]
	v_mfma_f32_16x16x32_bf16 v[6:9], v[146:149], v[210:213], v[6:9]
	v_mfma_f32_16x16x32_bf16 v[2:5], v[154:157], v[210:213], v[2:5]
	v_mfma_f32_16x16x32_bf16 v[30:33], v[150:153], v[166:169], v[30:33]
	v_mfma_f32_16x16x32_bf16 v[26:29], v[158:161], v[166:169], v[26:29]
	v_mfma_f32_16x16x32_bf16 v[22:25], v[150:153], v[174:177], v[22:25]
	v_mfma_f32_16x16x32_bf16 v[18:21], v[158:161], v[174:177], v[18:21]
	v_mfma_f32_16x16x32_bf16 v[14:17], v[150:153], v[206:209], v[14:17]
	v_mfma_f32_16x16x32_bf16 v[10:13], v[158:161], v[206:209], v[10:13]
	v_mfma_f32_16x16x32_bf16 v[6:9], v[150:153], v[214:217], v[6:9]
	v_mfma_f32_16x16x32_bf16 v[2:5], v[158:161], v[214:217], v[2:5]
	s_setprio 0
	s_barrier
	s_add_i32 s71, 0, 0x18000
	s_add_i32 s72, 0, 0x1c000
	s_add_u32 s34, s34, 0xc0000
	s_addc_u32 s35, s35, 0
	s_mov_b32 m0, s39
	s_nop 0
	global_load_lds_dwordx4 v184, s[34:35]
	s_mov_b32 m0, s40
	s_nop 0
	global_load_lds_dwordx4 v180, s[34:35]
	v_add_u32_e32 v142, s71, v200
	v_add_u32_e32 v158, s72, v200
	ds_read_b128 v[130:133], v142
	ds_read_b128 v[134:137], v142 offset:1024
	ds_read_b128 v[138:141], v142 offset:2048
	ds_read_b128 v[142:145], v142 offset:3072
	ds_read_b128 v[146:149], v158
	ds_read_b128 v[150:153], v158 offset:1024
	ds_read_b128 v[154:157], v158 offset:2048
	ds_read_b128 v[158:161], v158 offset:3072
	ds_read_b128 v[162:165], v201 offset:32768
	ds_read_b128 v[166:169], v201 offset:33792
	ds_read_b128 v[170:173], v201 offset:34816
	ds_read_b128 v[174:177], v201 offset:35840
	ds_read_b128 v[202:205], v201 offset:36864
	ds_read_b128 v[206:209], v201 offset:37888
	ds_read_b128 v[210:213], v201 offset:38912
	ds_read_b128 v[214:217], v201 offset:39936
	s_waitcnt vmcnt(8)
	s_waitcnt lgkmcnt(0)
	s_barrier
	s_setprio 1
	s_waitcnt lgkmcnt(0)
	v_mfma_f32_16x16x32_bf16 v[126:129], v[130:133], v[162:165], v[126:129]
	v_mfma_f32_16x16x32_bf16 v[122:125], v[138:141], v[162:165], v[122:125]
	v_mfma_f32_16x16x32_bf16 v[118:121], v[130:133], v[170:173], v[118:121]
	v_mfma_f32_16x16x32_bf16 v[114:117], v[138:141], v[170:173], v[114:117]
	v_mfma_f32_16x16x32_bf16 v[110:113], v[130:133], v[202:205], v[110:113]
	v_mfma_f32_16x16x32_bf16 v[106:109], v[138:141], v[202:205], v[106:109]
	v_mfma_f32_16x16x32_bf16 v[102:105], v[130:133], v[210:213], v[102:105]
	v_mfma_f32_16x16x32_bf16 v[98:101], v[138:141], v[210:213], v[98:101]
	v_mfma_f32_16x16x32_bf16 v[126:129], v[134:137], v[166:169], v[126:129]
	v_mfma_f32_16x16x32_bf16 v[122:125], v[142:145], v[166:169], v[122:125]
	v_mfma_f32_16x16x32_bf16 v[118:121], v[134:137], v[174:177], v[118:121]
	v_mfma_f32_16x16x32_bf16 v[114:117], v[142:145], v[174:177], v[114:117]
	v_mfma_f32_16x16x32_bf16 v[110:113], v[134:137], v[206:209], v[110:113]
	v_mfma_f32_16x16x32_bf16 v[106:109], v[142:145], v[206:209], v[106:109]
	v_mfma_f32_16x16x32_bf16 v[102:105], v[134:137], v[214:217], v[102:105]
	v_mfma_f32_16x16x32_bf16 v[98:101], v[142:145], v[214:217], v[98:101]
	s_setprio 0
	s_setprio 1
	v_mfma_f32_16x16x32_bf16 v[94:97], v[146:149], v[162:165], v[94:97]
	v_mfma_f32_16x16x32_bf16 v[90:93], v[154:157], v[162:165], v[90:93]
	v_mfma_f32_16x16x32_bf16 v[86:89], v[146:149], v[170:173], v[86:89]
	v_mfma_f32_16x16x32_bf16 v[82:85], v[154:157], v[170:173], v[82:85]
	v_mfma_f32_16x16x32_bf16 v[78:81], v[146:149], v[202:205], v[78:81]
	v_mfma_f32_16x16x32_bf16 v[74:77], v[154:157], v[202:205], v[74:77]
	v_mfma_f32_16x16x32_bf16 v[66:69], v[146:149], v[210:213], v[66:69]
	v_mfma_f32_16x16x32_bf16 v[58:61], v[154:157], v[210:213], v[58:61]
	v_mfma_f32_16x16x32_bf16 v[94:97], v[150:153], v[166:169], v[94:97]
	v_mfma_f32_16x16x32_bf16 v[90:93], v[158:161], v[166:169], v[90:93]
	v_mfma_f32_16x16x32_bf16 v[86:89], v[150:153], v[174:177], v[86:89]
	v_mfma_f32_16x16x32_bf16 v[82:85], v[158:161], v[174:177], v[82:85]
	v_mfma_f32_16x16x32_bf16 v[78:81], v[150:153], v[206:209], v[78:81]
	v_mfma_f32_16x16x32_bf16 v[74:77], v[158:161], v[206:209], v[74:77]
	v_mfma_f32_16x16x32_bf16 v[66:69], v[150:153], v[214:217], v[66:69]
	v_mfma_f32_16x16x32_bf16 v[58:61], v[158:161], v[214:217], v[58:61]
	s_setprio 0
	s_barrier
	s_add_u32 s34, s30, 0x4000
	s_addc_u32 s35, s31, 0
	s_add_i32 s71, s71, s36
	s_mov_b32 m0, s71
	s_nop 0
	global_load_lds_dwordx4 v182, s[34:35]
	s_add_i32 m0, s71, 0x2000
	s_add_u32 s30, s30, 0xc4000
	s_addc_u32 s31, s31, 0
	global_load_lds_dwordx4 v178, s[34:35]
	s_add_i32 s34, s72, s36
	s_mov_b32 m0, s34
	s_nop 0
	global_load_lds_dwordx4 v182, s[30:31]
	s_add_i32 m0, s34, 0x2000
	s_nop 0
	global_load_lds_dwordx4 v178, s[30:31]
	s_mov_b32 m0, s42
	s_nop 0
	global_load_lds_dwordx4 v184, s[26:27]
	s_mov_b32 m0, s43
	s_nop 0
	global_load_lds_dwordx4 v180, s[26:27]
	ds_read_b128 v[162:165], v201 offset:49152
	ds_read_b128 v[166:169], v201 offset:50176
	ds_read_b128 v[170:173], v201 offset:51200
	ds_read_b128 v[174:177], v201 offset:52224
	ds_read_b128 v[202:205], v201 offset:53248
	ds_read_b128 v[206:209], v201 offset:54272
	ds_read_b128 v[210:213], v201 offset:55296
	ds_read_b128 v[214:217], v201 offset:56320
	s_waitcnt vmcnt(8)
	s_waitcnt lgkmcnt(0)
	s_barrier
	s_setprio 1
	s_waitcnt lgkmcnt(0)
	v_mfma_f32_16x16x32_bf16 v[70:73], v[130:133], v[162:165], v[70:73]
	v_mfma_f32_16x16x32_bf16 v[62:65], v[138:141], v[162:165], v[62:65]
	v_mfma_f32_16x16x32_bf16 v[54:57], v[130:133], v[170:173], v[54:57]
	v_mfma_f32_16x16x32_bf16 v[50:53], v[138:141], v[170:173], v[50:53]
	v_mfma_f32_16x16x32_bf16 v[46:49], v[130:133], v[202:205], v[46:49]
	v_mfma_f32_16x16x32_bf16 v[42:45], v[138:141], v[202:205], v[42:45]
	v_mfma_f32_16x16x32_bf16 v[38:41], v[130:133], v[210:213], v[38:41]
	v_mfma_f32_16x16x32_bf16 v[34:37], v[138:141], v[210:213], v[34:37]
	v_mfma_f32_16x16x32_bf16 v[70:73], v[134:137], v[166:169], v[70:73]
	v_mfma_f32_16x16x32_bf16 v[62:65], v[142:145], v[166:169], v[62:65]
	v_mfma_f32_16x16x32_bf16 v[54:57], v[134:137], v[174:177], v[54:57]
	v_mfma_f32_16x16x32_bf16 v[50:53], v[142:145], v[174:177], v[50:53]
	v_mfma_f32_16x16x32_bf16 v[46:49], v[134:137], v[206:209], v[46:49]
	v_mfma_f32_16x16x32_bf16 v[42:45], v[142:145], v[206:209], v[42:45]
	v_mfma_f32_16x16x32_bf16 v[38:41], v[134:137], v[214:217], v[38:41]
	v_mfma_f32_16x16x32_bf16 v[34:37], v[142:145], v[214:217], v[34:37]
	s_setprio 0
	s_setprio 1
	v_mfma_f32_16x16x32_bf16 v[30:33], v[146:149], v[162:165], v[30:33]
	v_mfma_f32_16x16x32_bf16 v[26:29], v[154:157], v[162:165], v[26:29]
	v_mfma_f32_16x16x32_bf16 v[22:25], v[146:149], v[170:173], v[22:25]
	v_mfma_f32_16x16x32_bf16 v[18:21], v[154:157], v[170:173], v[18:21]
	v_mfma_f32_16x16x32_bf16 v[14:17], v[146:149], v[202:205], v[14:17]
	v_mfma_f32_16x16x32_bf16 v[10:13], v[154:157], v[202:205], v[10:13]
	v_mfma_f32_16x16x32_bf16 v[6:9], v[146:149], v[210:213], v[6:9]
	v_mfma_f32_16x16x32_bf16 v[2:5], v[154:157], v[210:213], v[2:5]
	v_mfma_f32_16x16x32_bf16 v[30:33], v[150:153], v[166:169], v[30:33]
	v_mfma_f32_16x16x32_bf16 v[26:29], v[158:161], v[166:169], v[26:29]
	v_mfma_f32_16x16x32_bf16 v[22:25], v[150:153], v[174:177], v[22:25]
	v_mfma_f32_16x16x32_bf16 v[18:21], v[158:161], v[174:177], v[18:21]
	v_mfma_f32_16x16x32_bf16 v[14:17], v[150:153], v[206:209], v[14:17]
	v_mfma_f32_16x16x32_bf16 v[10:13], v[158:161], v[206:209], v[10:13]
	v_mfma_f32_16x16x32_bf16 v[6:9], v[150:153], v[214:217], v[6:9]
	v_mfma_f32_16x16x32_bf16 v[2:5], v[158:161], v[214:217], v[2:5]
	s_setprio 0
	s_barrier
	s_add_u32 s24, s24, 0x8000
	s_addc_u32 s25, s25, 0
	s_add_u32 s68, s68, 0x8000
	s_addc_u32 s69, s69, 0
	s_cmp_ge_u32 s70, s66
	s_mov_b32 s31, s70
	s_cbranch_scc0 .LBB0_1005
	s_and_b64 vcc, exec, s[18:19]
	s_cbranch_vccnz .LBB0_1010
	v_lshl_add_u32 v162, s65, 8, v189
	s_mov_b64 s[24:25], -1
	s_and_b64 vcc, exec, s[22:23]
	s_cbranch_vccnz .LBB0_1011

.LBB0_1088:
	s_add_u32 s38, s36, 0xfff04000
	s_addc_u32 s39, s37, -1
	s_cmp_eq_u32 s72, 60
	s_cselect_b32 s42, s35, s38
	s_cselect_b32 s43, s25, s39
	s_cselect_b32 s40, s69, s70
	s_cselect_b32 s41, s23, s71
	s_add_u32 s38, s42, 0x4000
	s_addc_u32 s39, s43, 0
	s_add_i32 m0, s47, 0xc000
	s_nop 0
	global_load_lds_dwordx4 v188, s[36:37]
	s_add_i32 m0, s47, 0xe000
	s_nop 0
	global_load_lds_dwordx4 v190, s[36:37]
	ds_read_b128 v[130:133], v209
	ds_read_b128 v[134:137], v209 offset:1024
	ds_read_b128 v[138:141], v209 offset:2048
	ds_read_b128 v[142:145], v209 offset:3072
	ds_read_b128 v[146:149], v210
	ds_read_b128 v[150:153], v210 offset:1024
	ds_read_b128 v[154:157], v210 offset:2048
	ds_read_b128 v[158:161], v210 offset:3072
	ds_read_b128 v[162:165], v211
	ds_read_b128 v[166:169], v211 offset:1024
	ds_read_b128 v[170:173], v211 offset:2048
	ds_read_b128 v[174:177], v211 offset:3072
	ds_read_b128 v[196:199], v211 offset:4096
	ds_read_b128 v[200:203], v211 offset:5120
	ds_read_b128 v[214:217], v211 offset:6144
	ds_read_b128 v[218:221], v211 offset:7168
	s_waitcnt vmcnt(8)
	s_waitcnt lgkmcnt(0)
	s_barrier
	s_setprio 1
	s_waitcnt lgkmcnt(0)
	v_mfma_f32_16x16x32_bf16 v[126:129], v[130:133], v[162:165], v[126:129]
	v_mfma_f32_16x16x32_bf16 v[122:125], v[138:141], v[162:165], v[122:125]
	v_mfma_f32_16x16x32_bf16 v[110:113], v[130:133], v[170:173], v[110:113]
	v_mfma_f32_16x16x32_bf16 v[106:109], v[138:141], v[170:173], v[106:109]
	v_mfma_f32_16x16x32_bf16 v[94:97], v[130:133], v[196:199], v[94:97]
	v_mfma_f32_16x16x32_bf16 v[90:93], v[138:141], v[196:199], v[90:93]
	v_mfma_f32_16x16x32_bf16 v[78:81], v[130:133], v[214:217], v[78:81]
	v_mfma_f32_16x16x32_bf16 v[74:77], v[138:141], v[214:217], v[74:77]
	v_mfma_f32_16x16x32_bf16 v[126:129], v[134:137], v[166:169], v[126:129]
	v_mfma_f32_16x16x32_bf16 v[122:125], v[142:145], v[166:169], v[122:125]
	v_mfma_f32_16x16x32_bf16 v[110:113], v[134:137], v[174:177], v[110:113]
	v_mfma_f32_16x16x32_bf16 v[106:109], v[142:145], v[174:177], v[106:109]
	v_mfma_f32_16x16x32_bf16 v[94:97], v[134:137], v[200:203], v[94:97]
	v_mfma_f32_16x16x32_bf16 v[90:93], v[142:145], v[200:203], v[90:93]
	v_mfma_f32_16x16x32_bf16 v[78:81], v[134:137], v[218:221], v[78:81]
	v_mfma_f32_16x16x32_bf16 v[74:77], v[142:145], v[218:221], v[74:77]
	s_setprio 0
	s_setprio 1
	v_mfma_f32_16x16x32_bf16 v[118:121], v[146:149], v[162:165], v[118:121]
	v_mfma_f32_16x16x32_bf16 v[114:117], v[154:157], v[162:165], v[114:117]
	v_mfma_f32_16x16x32_bf16 v[102:105], v[146:149], v[170:173], v[102:105]
	v_mfma_f32_16x16x32_bf16 v[98:101], v[154:157], v[170:173], v[98:101]
	v_mfma_f32_16x16x32_bf16 v[86:89], v[146:149], v[196:199], v[86:89]
	v_mfma_f32_16x16x32_bf16 v[82:85], v[154:157], v[196:199], v[82:85]
	v_mfma_f32_16x16x32_bf16 v[70:73], v[146:149], v[214:217], v[70:73]
	v_mfma_f32_16x16x32_bf16 v[66:69], v[154:157], v[214:217], v[66:69]
	v_mfma_f32_16x16x32_bf16 v[118:121], v[150:153], v[166:169], v[118:121]
	v_mfma_f32_16x16x32_bf16 v[114:117], v[158:161], v[166:169], v[114:117]
	v_mfma_f32_16x16x32_bf16 v[102:105], v[150:153], v[174:177], v[102:105]
	v_mfma_f32_16x16x32_bf16 v[98:101], v[158:161], v[174:177], v[98:101]
	v_mfma_f32_16x16x32_bf16 v[86:89], v[150:153], v[200:203], v[86:89]
	v_mfma_f32_16x16x32_bf16 v[82:85], v[158:161], v[200:203], v[82:85]
	v_mfma_f32_16x16x32_bf16 v[70:73], v[150:153], v[218:221], v[70:73]
	v_mfma_f32_16x16x32_bf16 v[66:69], v[158:161], v[218:221], v[66:69]
	s_setprio 0
	s_barrier
	s_add_i32 s73, s66, s46
	s_mov_b32 m0, s73
	s_nop 0
	global_load_lds_dwordx4 v180, s[40:41]
	s_add_i32 m0, s73, 0x2000
	s_add_u32 s74, s40, 0x100000
	s_addc_u32 s75, s41, 0
	s_add_i32 s73, s67, s46
	global_load_lds_dwordx4 v184, s[40:41]
	s_mov_b32 m0, s73
	s_nop 0
	global_load_lds_dwordx4 v180, s[74:75]
	s_add_i32 m0, s73, 0x2000
	s_nop 0
	global_load_lds_dwordx4 v184, s[74:75]
	s_mov_b32 m0, s47
	s_nop 0
	global_load_lds_dwordx4 v178, s[42:43]
	s_mov_b32 m0, s59
	s_nop 0
	global_load_lds_dwordx4 v182, s[42:43]
	ds_read_b128 v[162:165], v211 offset:16384
	ds_read_b128 v[166:169], v211 offset:17408
	ds_read_b128 v[170:173], v211 offset:18432
	ds_read_b128 v[174:177], v211 offset:19456
	ds_read_b128 v[196:199], v211 offset:20480
	ds_read_b128 v[200:203], v211 offset:21504
	ds_read_b128 v[214:217], v211 offset:22528
	ds_read_b128 v[218:221], v211 offset:23552
	s_waitcnt vmcnt(8)
	s_waitcnt lgkmcnt(0)
	s_barrier
	s_setprio 1
	s_waitcnt lgkmcnt(0)
	v_mfma_f32_16x16x32_bf16 v[62:65], v[130:133], v[162:165], v[62:65]
	v_mfma_f32_16x16x32_bf16 v[58:61], v[138:141], v[162:165], v[58:61]
	v_mfma_f32_16x16x32_bf16 v[46:49], v[130:133], v[170:173], v[46:49]
	v_mfma_f32_16x16x32_bf16 v[42:45], v[138:141], v[170:173], v[42:45]
	v_mfma_f32_16x16x32_bf16 v[30:33], v[130:133], v[196:199], v[30:33]
	v_mfma_f32_16x16x32_bf16 v[26:29], v[138:141], v[196:199], v[26:29]
	v_mfma_f32_16x16x32_bf16 v[14:17], v[130:133], v[214:217], v[14:17]
	v_mfma_f32_16x16x32_bf16 v[10:13], v[138:141], v[214:217], v[10:13]
	v_mfma_f32_16x16x32_bf16 v[62:65], v[134:137], v[166:169], v[62:65]
	v_mfma_f32_16x16x32_bf16 v[58:61], v[142:145], v[166:169], v[58:61]
	v_mfma_f32_16x16x32_bf16 v[46:49], v[134:137], v[174:177], v[46:49]
	v_mfma_f32_16x16x32_bf16 v[42:45], v[142:145], v[174:177], v[42:45]
	v_mfma_f32_16x16x32_bf16 v[30:33], v[134:137], v[200:203], v[30:33]
	v_mfma_f32_16x16x32_bf16 v[26:29], v[142:145], v[200:203], v[26:29]
	v_mfma_f32_16x16x32_bf16 v[14:17], v[134:137], v[218:221], v[14:17]
	v_mfma_f32_16x16x32_bf16 v[10:13], v[142:145], v[218:221], v[10:13]
	s_setprio 0
	s_setprio 1
	v_mfma_f32_16x16x32_bf16 v[54:57], v[146:149], v[162:165], v[54:57]
	v_mfma_f32_16x16x32_bf16 v[50:53], v[154:157], v[162:165], v[50:53]
	v_mfma_f32_16x16x32_bf16 v[38:41], v[146:149], v[170:173], v[38:41]
	v_mfma_f32_16x16x32_bf16 v[34:37], v[154:157], v[170:173], v[34:37]
	v_mfma_f32_16x16x32_bf16 v[22:25], v[146:149], v[196:199], v[22:25]
	v_mfma_f32_16x16x32_bf16 v[18:21], v[154:157], v[196:199], v[18:21]
	v_mfma_f32_16x16x32_bf16 v[6:9], v[146:149], v[214:217], v[6:9]
	v_mfma_f32_16x16x32_bf16 v[2:5], v[154:157], v[214:217], v[2:5]
	v_mfma_f32_16x16x32_bf16 v[54:57], v[150:153], v[166:169], v[54:57]
	v_mfma_f32_16x16x32_bf16 v[50:53], v[158:161], v[166:169], v[50:53]
	v_mfma_f32_16x16x32_bf16 v[38:41], v[150:153], v[174:177], v[38:41]
	v_mfma_f32_16x16x32_bf16 v[34:37], v[158:161], v[174:177], v[34:37]
	v_mfma_f32_16x16x32_bf16 v[22:25], v[150:153], v[200:203], v[22:25]
	v_mfma_f32_16x16x32_bf16 v[18:21], v[158:161], v[200:203], v[18:21]
	v_mfma_f32_16x16x32_bf16 v[6:9], v[150:153], v[218:221], v[6:9]
	v_mfma_f32_16x16x32_bf16 v[2:5], v[158:161], v[218:221], v[2:5]
	s_setprio 0
	s_barrier
	s_add_i32 s73, 0, 0x18000
	s_add_i32 s74, 0, 0x1c000
	s_add_u32 s42, s42, 0x100000
	s_addc_u32 s43, s43, 0
	s_mov_b32 m0, s60
	s_nop 0
	global_load_lds_dwordx4 v178, s[42:43]
	s_mov_b32 m0, s61
	s_nop 0
	global_load_lds_dwordx4 v182, s[42:43]
	v_add_u32_e32 v142, s73, v208
	v_add_u32_e32 v158, s74, v208
	ds_read_b128 v[130:133], v142
	ds_read_b128 v[134:137], v142 offset:1024
	ds_read_b128 v[138:141], v142 offset:2048
	ds_read_b128 v[142:145], v142 offset:3072
	ds_read_b128 v[146:149], v158
	ds_read_b128 v[150:153], v158 offset:1024
	ds_read_b128 v[154:157], v158 offset:2048
	ds_read_b128 v[158:161], v158 offset:3072
	ds_read_b128 v[162:165], v211 offset:32768
	ds_read_b128 v[166:169], v211 offset:33792
	ds_read_b128 v[170:173], v211 offset:34816
	ds_read_b128 v[174:177], v211 offset:35840
	ds_read_b128 v[196:199], v211 offset:36864
	ds_read_b128 v[200:203], v211 offset:37888
	ds_read_b128 v[214:217], v211 offset:38912
	ds_read_b128 v[218:221], v211 offset:39936
	s_waitcnt vmcnt(8)
	s_waitcnt lgkmcnt(0)
	s_barrier
	s_setprio 1
	s_waitcnt lgkmcnt(0)
	v_mfma_f32_16x16x32_bf16 v[126:129], v[130:133], v[162:165], v[126:129]
	v_mfma_f32_16x16x32_bf16 v[122:125], v[138:141], v[162:165], v[122:125]
	v_mfma_f32_16x16x32_bf16 v[110:113], v[130:133], v[170:173], v[110:113]
	v_mfma_f32_16x16x32_bf16 v[106:109], v[138:141], v[170:173], v[106:109]
	v_mfma_f32_16x16x32_bf16 v[94:97], v[130:133], v[196:199], v[94:97]
	v_mfma_f32_16x16x32_bf16 v[90:93], v[138:141], v[196:199], v[90:93]
	v_mfma_f32_16x16x32_bf16 v[78:81], v[130:133], v[214:217], v[78:81]
	v_mfma_f32_16x16x32_bf16 v[74:77], v[138:141], v[214:217], v[74:77]
	v_mfma_f32_16x16x32_bf16 v[126:129], v[134:137], v[166:169], v[126:129]
	v_mfma_f32_16x16x32_bf16 v[122:125], v[142:145], v[166:169], v[122:125]
	v_mfma_f32_16x16x32_bf16 v[110:113], v[134:137], v[174:177], v[110:113]
	v_mfma_f32_16x16x32_bf16 v[106:109], v[142:145], v[174:177], v[106:109]
	v_mfma_f32_16x16x32_bf16 v[94:97], v[134:137], v[200:203], v[94:97]
	v_mfma_f32_16x16x32_bf16 v[90:93], v[142:145], v[200:203], v[90:93]
	v_mfma_f32_16x16x32_bf16 v[78:81], v[134:137], v[218:221], v[78:81]
	v_mfma_f32_16x16x32_bf16 v[74:77], v[142:145], v[218:221], v[74:77]
	s_setprio 0
	s_setprio 1
	v_mfma_f32_16x16x32_bf16 v[118:121], v[146:149], v[162:165], v[118:121]
	v_mfma_f32_16x16x32_bf16 v[114:117], v[154:157], v[162:165], v[114:117]
	v_mfma_f32_16x16x32_bf16 v[102:105], v[146:149], v[170:173], v[102:105]
	v_mfma_f32_16x16x32_bf16 v[98:101], v[154:157], v[170:173], v[98:101]
	v_mfma_f32_16x16x32_bf16 v[86:89], v[146:149], v[196:199], v[86:89]
	v_mfma_f32_16x16x32_bf16 v[82:85], v[154:157], v[196:199], v[82:85]
	v_mfma_f32_16x16x32_bf16 v[70:73], v[146:149], v[214:217], v[70:73]
	v_mfma_f32_16x16x32_bf16 v[66:69], v[154:157], v[214:217], v[66:69]
	v_mfma_f32_16x16x32_bf16 v[118:121], v[150:153], v[166:169], v[118:121]
	v_mfma_f32_16x16x32_bf16 v[114:117], v[158:161], v[166:169], v[114:117]
	v_mfma_f32_16x16x32_bf16 v[102:105], v[150:153], v[174:177], v[102:105]
	v_mfma_f32_16x16x32_bf16 v[98:101], v[158:161], v[174:177], v[98:101]
	v_mfma_f32_16x16x32_bf16 v[86:89], v[150:153], v[200:203], v[86:89]
	v_mfma_f32_16x16x32_bf16 v[82:85], v[158:161], v[200:203], v[82:85]
	v_mfma_f32_16x16x32_bf16 v[70:73], v[150:153], v[218:221], v[70:73]
	v_mfma_f32_16x16x32_bf16 v[66:69], v[158:161], v[218:221], v[66:69]
	s_setprio 0
	s_barrier
	s_add_u32 s42, s40, 0x4000
	s_addc_u32 s43, s41, 0
	s_add_i32 s73, s73, s46
	s_mov_b32 m0, s73
	s_nop 0
	global_load_lds_dwordx4 v180, s[42:43]
	s_add_i32 m0, s73, 0x2000
	s_add_u32 s40, s40, 0x104000
	s_addc_u32 s41, s41, 0
	global_load_lds_dwordx4 v184, s[42:43]
	s_add_i32 s42, s74, s46
	s_mov_b32 m0, s42
	s_nop 0
	global_load_lds_dwordx4 v180, s[40:41]
	s_add_i32 m0, s42, 0x2000
	s_nop 0
	global_load_lds_dwordx4 v184, s[40:41]
	s_mov_b32 m0, s64
	s_nop 0
	global_load_lds_dwordx4 v178, s[38:39]
	s_mov_b32 m0, s65
	s_nop 0
	global_load_lds_dwordx4 v182, s[38:39]
	ds_read_b128 v[162:165], v211 offset:49152
	ds_read_b128 v[166:169], v211 offset:50176
	ds_read_b128 v[170:173], v211 offset:51200
	ds_read_b128 v[174:177], v211 offset:52224
	ds_read_b128 v[196:199], v211 offset:53248
	ds_read_b128 v[200:203], v211 offset:54272
	ds_read_b128 v[214:217], v211 offset:55296
	ds_read_b128 v[218:221], v211 offset:56320
	s_waitcnt vmcnt(8)
	s_waitcnt lgkmcnt(0)
	s_barrier
	s_setprio 1
	s_waitcnt lgkmcnt(0)
	v_mfma_f32_16x16x32_bf16 v[62:65], v[130:133], v[162:165], v[62:65]
	v_mfma_f32_16x16x32_bf16 v[58:61], v[138:141], v[162:165], v[58:61]
	v_mfma_f32_16x16x32_bf16 v[46:49], v[130:133], v[170:173], v[46:49]
	v_mfma_f32_16x16x32_bf16 v[42:45], v[138:141], v[170:173], v[42:45]
	v_mfma_f32_16x16x32_bf16 v[30:33], v[130:133], v[196:199], v[30:33]
	v_mfma_f32_16x16x32_bf16 v[26:29], v[138:141], v[196:199], v[26:29]
	v_mfma_f32_16x16x32_bf16 v[14:17], v[130:133], v[214:217], v[14:17]
	v_mfma_f32_16x16x32_bf16 v[10:13], v[138:141], v[214:217], v[10:13]
	v_mfma_f32_16x16x32_bf16 v[62:65], v[134:137], v[166:169], v[62:65]
	v_mfma_f32_16x16x32_bf16 v[58:61], v[142:145], v[166:169], v[58:61]
	v_mfma_f32_16x16x32_bf16 v[46:49], v[134:137], v[174:177], v[46:49]
	v_mfma_f32_16x16x32_bf16 v[42:45], v[142:145], v[174:177], v[42:45]
	v_mfma_f32_16x16x32_bf16 v[30:33], v[134:137], v[200:203], v[30:33]
	v_mfma_f32_16x16x32_bf16 v[26:29], v[142:145], v[200:203], v[26:29]
	v_mfma_f32_16x16x32_bf16 v[14:17], v[134:137], v[218:221], v[14:17]
	v_mfma_f32_16x16x32_bf16 v[10:13], v[142:145], v[218:221], v[10:13]
	s_setprio 0
	s_setprio 1
	v_mfma_f32_16x16x32_bf16 v[54:57], v[146:149], v[162:165], v[54:57]
	v_mfma_f32_16x16x32_bf16 v[50:53], v[154:157], v[162:165], v[50:53]
	v_mfma_f32_16x16x32_bf16 v[38:41], v[146:149], v[170:173], v[38:41]
	v_mfma_f32_16x16x32_bf16 v[34:37], v[154:157], v[170:173], v[34:37]
	v_mfma_f32_16x16x32_bf16 v[22:25], v[146:149], v[196:199], v[22:25]
	v_mfma_f32_16x16x32_bf16 v[18:21], v[154:157], v[196:199], v[18:21]
	v_mfma_f32_16x16x32_bf16 v[6:9], v[146:149], v[214:217], v[6:9]
	v_mfma_f32_16x16x32_bf16 v[2:5], v[154:157], v[214:217], v[2:5]
	v_mfma_f32_16x16x32_bf16 v[54:57], v[150:153], v[166:169], v[54:57]
	v_mfma_f32_16x16x32_bf16 v[50:53], v[158:161], v[166:169], v[50:53]
	v_mfma_f32_16x16x32_bf16 v[38:41], v[150:153], v[174:177], v[38:41]
	v_mfma_f32_16x16x32_bf16 v[34:37], v[158:161], v[174:177], v[34:37]
	v_mfma_f32_16x16x32_bf16 v[22:25], v[150:153], v[200:203], v[22:25]
	v_mfma_f32_16x16x32_bf16 v[18:21], v[158:161], v[200:203], v[18:21]
	v_mfma_f32_16x16x32_bf16 v[6:9], v[150:153], v[218:221], v[6:9]
	v_mfma_f32_16x16x32_bf16 v[2:5], v[158:161], v[218:221], v[2:5]
	s_setprio 0
	s_barrier
	s_add_i32 s72, s72, 2
	s_add_u32 s36, s36, 0x8000
	s_addc_u32 s37, s37, 0
	s_add_u32 s70, s70, 0x8000
	s_addc_u32 s71, s71, 0
	s_cmp_gt_u32 s72, 61
	s_cbranch_scc0 .LBB0_1088
	s_and_b64 vcc, exec, s[20:21]
	s_cbranch_vccz .LBB0_1091
	s_barrier

.LBB0_1215:
	s_add_u32 s30, s28, 0xfff04000
	s_addc_u32 s31, s29, -1
	s_cmp_eq_u32 s61, 60
	s_cselect_b32 s36, s56, s30
	s_cselect_b32 s37, s21, s31
	s_cselect_b32 s34, s57, s59
	s_cselect_b32 s35, s19, s60
	s_add_u32 s30, s36, 0x4000
	s_addc_u32 s31, s37, 0
	s_add_i32 m0, s39, 0xc000
	s_nop 0
	global_load_lds_dwordx4 v140, s[28:29]
	s_add_i32 m0, s39, 0xe000
	s_nop 0
	global_load_lds_dwordx4 v142, s[28:29]
	ds_read_b128 v[160:163], v154
	ds_read_b128 v[164:167], v154 offset:1024
	ds_read_b128 v[168:171], v154 offset:2048
	ds_read_b128 v[172:175], v154 offset:3072
	ds_read_b128 v[176:179], v155
	ds_read_b128 v[180:183], v155 offset:1024
	ds_read_b128 v[184:187], v155 offset:2048
	ds_read_b128 v[188:191], v155 offset:3072
	ds_read_b128 v[192:195], v156
	ds_read_b128 v[196:199], v156 offset:1024
	ds_read_b128 v[200:203], v156 offset:2048
	ds_read_b128 v[204:207], v156 offset:3072
	ds_read_b128 v[208:211], v156 offset:4096
	ds_read_b128 v[212:215], v156 offset:5120
	ds_read_b128 v[216:219], v156 offset:6144
	ds_read_b128 v[220:223], v156 offset:7168
	s_waitcnt vmcnt(8)
	s_waitcnt lgkmcnt(0)
	s_barrier
	s_setprio 1
	s_waitcnt lgkmcnt(0)
	v_mfma_f32_16x16x32_bf16 v[126:129], v[160:163], v[192:195], v[126:129]
	v_mfma_f32_16x16x32_bf16 v[122:125], v[168:171], v[192:195], v[122:125]
	v_mfma_f32_16x16x32_bf16 v[110:113], v[160:163], v[200:203], v[110:113]
	v_mfma_f32_16x16x32_bf16 v[106:109], v[168:171], v[200:203], v[106:109]
	v_mfma_f32_16x16x32_bf16 v[94:97], v[160:163], v[208:211], v[94:97]
	v_mfma_f32_16x16x32_bf16 v[90:93], v[168:171], v[208:211], v[90:93]
	v_mfma_f32_16x16x32_bf16 v[78:81], v[160:163], v[216:219], v[78:81]
	v_mfma_f32_16x16x32_bf16 v[74:77], v[168:171], v[216:219], v[74:77]
	v_mfma_f32_16x16x32_bf16 v[126:129], v[164:167], v[196:199], v[126:129]
	v_mfma_f32_16x16x32_bf16 v[122:125], v[172:175], v[196:199], v[122:125]
	v_mfma_f32_16x16x32_bf16 v[110:113], v[164:167], v[204:207], v[110:113]
	v_mfma_f32_16x16x32_bf16 v[106:109], v[172:175], v[204:207], v[106:109]
	v_mfma_f32_16x16x32_bf16 v[94:97], v[164:167], v[212:215], v[94:97]
	v_mfma_f32_16x16x32_bf16 v[90:93], v[172:175], v[212:215], v[90:93]
	v_mfma_f32_16x16x32_bf16 v[78:81], v[164:167], v[220:223], v[78:81]
	v_mfma_f32_16x16x32_bf16 v[74:77], v[172:175], v[220:223], v[74:77]
	s_setprio 0
	s_setprio 1
	v_mfma_f32_16x16x32_bf16 v[118:121], v[176:179], v[192:195], v[118:121]
	v_mfma_f32_16x16x32_bf16 v[114:117], v[184:187], v[192:195], v[114:117]
	v_mfma_f32_16x16x32_bf16 v[102:105], v[176:179], v[200:203], v[102:105]
	v_mfma_f32_16x16x32_bf16 v[98:101], v[184:187], v[200:203], v[98:101]
	v_mfma_f32_16x16x32_bf16 v[86:89], v[176:179], v[208:211], v[86:89]
	v_mfma_f32_16x16x32_bf16 v[82:85], v[184:187], v[208:211], v[82:85]
	v_mfma_f32_16x16x32_bf16 v[70:73], v[176:179], v[216:219], v[70:73]
	v_mfma_f32_16x16x32_bf16 v[66:69], v[184:187], v[216:219], v[66:69]
	v_mfma_f32_16x16x32_bf16 v[118:121], v[180:183], v[196:199], v[118:121]
	v_mfma_f32_16x16x32_bf16 v[114:117], v[188:191], v[196:199], v[114:117]
	v_mfma_f32_16x16x32_bf16 v[102:105], v[180:183], v[204:207], v[102:105]
	v_mfma_f32_16x16x32_bf16 v[98:101], v[188:191], v[204:207], v[98:101]
	v_mfma_f32_16x16x32_bf16 v[86:89], v[180:183], v[212:215], v[86:89]
	v_mfma_f32_16x16x32_bf16 v[82:85], v[188:191], v[212:215], v[82:85]
	v_mfma_f32_16x16x32_bf16 v[70:73], v[180:183], v[220:223], v[70:73]
	v_mfma_f32_16x16x32_bf16 v[66:69], v[188:191], v[220:223], v[66:69]
	s_setprio 0
	s_barrier
	s_add_i32 s62, s47, s38
	s_mov_b32 m0, s62
	s_nop 0
	global_load_lds_dwordx4 v134, s[34:35]
	s_add_i32 m0, s62, 0x2000
	s_add_u32 s62, s34, 0x100000
	s_addc_u32 s63, s35, 0
	s_add_i32 s64, s54, s38
	global_load_lds_dwordx4 v130, s[34:35]
	s_mov_b32 m0, s64
	s_nop 0
	global_load_lds_dwordx4 v134, s[62:63]
	s_add_i32 m0, s64, 0x2000
	s_nop 0
	global_load_lds_dwordx4 v130, s[62:63]
	s_mov_b32 m0, s39
	s_nop 0
	global_load_lds_dwordx4 v136, s[36:37]
	s_mov_b32 m0, s40
	s_nop 0
	global_load_lds_dwordx4 v132, s[36:37]
	ds_read_b128 v[192:195], v156 offset:16384
	ds_read_b128 v[196:199], v156 offset:17408
	ds_read_b128 v[200:203], v156 offset:18432
	ds_read_b128 v[204:207], v156 offset:19456
	ds_read_b128 v[208:211], v156 offset:20480
	ds_read_b128 v[212:215], v156 offset:21504
	ds_read_b128 v[216:219], v156 offset:22528
	ds_read_b128 v[220:223], v156 offset:23552
	s_waitcnt vmcnt(8)
	s_waitcnt lgkmcnt(0)
	s_barrier
	s_setprio 1
	s_waitcnt lgkmcnt(0)
	v_mfma_f32_16x16x32_bf16 v[62:65], v[160:163], v[192:195], v[62:65]
	v_mfma_f32_16x16x32_bf16 v[58:61], v[168:171], v[192:195], v[58:61]
	v_mfma_f32_16x16x32_bf16 v[46:49], v[160:163], v[200:203], v[46:49]
	v_mfma_f32_16x16x32_bf16 v[42:45], v[168:171], v[200:203], v[42:45]
	v_mfma_f32_16x16x32_bf16 v[30:33], v[160:163], v[208:211], v[30:33]
	v_mfma_f32_16x16x32_bf16 v[26:29], v[168:171], v[208:211], v[26:29]
	v_mfma_f32_16x16x32_bf16 v[14:17], v[160:163], v[216:219], v[14:17]
	v_mfma_f32_16x16x32_bf16 v[10:13], v[168:171], v[216:219], v[10:13]
	v_mfma_f32_16x16x32_bf16 v[62:65], v[164:167], v[196:199], v[62:65]
	v_mfma_f32_16x16x32_bf16 v[58:61], v[172:175], v[196:199], v[58:61]
	v_mfma_f32_16x16x32_bf16 v[46:49], v[164:167], v[204:207], v[46:49]
	v_mfma_f32_16x16x32_bf16 v[42:45], v[172:175], v[204:207], v[42:45]
	v_mfma_f32_16x16x32_bf16 v[30:33], v[164:167], v[212:215], v[30:33]
	v_mfma_f32_16x16x32_bf16 v[26:29], v[172:175], v[212:215], v[26:29]
	v_mfma_f32_16x16x32_bf16 v[14:17], v[164:167], v[220:223], v[14:17]
	v_mfma_f32_16x16x32_bf16 v[10:13], v[172:175], v[220:223], v[10:13]
	s_setprio 0
	s_setprio 1
	v_mfma_f32_16x16x32_bf16 v[54:57], v[176:179], v[192:195], v[54:57]
	v_mfma_f32_16x16x32_bf16 v[50:53], v[184:187], v[192:195], v[50:53]
	v_mfma_f32_16x16x32_bf16 v[38:41], v[176:179], v[200:203], v[38:41]
	v_mfma_f32_16x16x32_bf16 v[34:37], v[184:187], v[200:203], v[34:37]
	v_mfma_f32_16x16x32_bf16 v[22:25], v[176:179], v[208:211], v[22:25]
	v_mfma_f32_16x16x32_bf16 v[18:21], v[184:187], v[208:211], v[18:21]
	v_mfma_f32_16x16x32_bf16 v[6:9], v[176:179], v[216:219], v[6:9]
	v_mfma_f32_16x16x32_bf16 v[2:5], v[184:187], v[216:219], v[2:5]
	v_mfma_f32_16x16x32_bf16 v[54:57], v[180:183], v[196:199], v[54:57]
	v_mfma_f32_16x16x32_bf16 v[50:53], v[188:191], v[196:199], v[50:53]
	v_mfma_f32_16x16x32_bf16 v[38:41], v[180:183], v[204:207], v[38:41]
	v_mfma_f32_16x16x32_bf16 v[34:37], v[188:191], v[204:207], v[34:37]
	v_mfma_f32_16x16x32_bf16 v[22:25], v[180:183], v[212:215], v[22:25]
	v_mfma_f32_16x16x32_bf16 v[18:21], v[188:191], v[212:215], v[18:21]
	v_mfma_f32_16x16x32_bf16 v[6:9], v[180:183], v[220:223], v[6:9]
	v_mfma_f32_16x16x32_bf16 v[2:5], v[188:191], v[220:223], v[2:5]
	s_setprio 0
	s_barrier
	s_add_i32 s62, 0, 0x18000
	s_add_i32 s63, 0, 0x1c000
	s_add_u32 s36, s36, 0x100000
	s_addc_u32 s37, s37, 0
	s_mov_b32 m0, s41
	s_nop 0
	global_load_lds_dwordx4 v136, s[36:37]
	s_mov_b32 m0, s42
	s_nop 0
	global_load_lds_dwordx4 v132, s[36:37]
	v_add_u32_e32 v138, s62, v153
	ds_read_b128 v[160:163], v138
	ds_read_b128 v[164:167], v138 offset:1024
	ds_read_b128 v[168:171], v138 offset:2048
	ds_read_b128 v[172:175], v138 offset:3072
	v_add_u32_e32 v138, s63, v153
	ds_read_b128 v[176:179], v138
	ds_read_b128 v[180:183], v138 offset:1024
	ds_read_b128 v[184:187], v138 offset:2048
	ds_read_b128 v[188:191], v138 offset:3072
	ds_read_b128 v[192:195], v156 offset:32768
	ds_read_b128 v[196:199], v156 offset:33792
	ds_read_b128 v[200:203], v156 offset:34816
	ds_read_b128 v[204:207], v156 offset:35840
	ds_read_b128 v[208:211], v156 offset:36864
	ds_read_b128 v[212:215], v156 offset:37888
	ds_read_b128 v[216:219], v156 offset:38912
	ds_read_b128 v[220:223], v156 offset:39936
	s_waitcnt vmcnt(8)
	s_waitcnt lgkmcnt(0)
	s_barrier
	s_setprio 1
	s_waitcnt lgkmcnt(0)
	v_mfma_f32_16x16x32_bf16 v[126:129], v[160:163], v[192:195], v[126:129]
	v_mfma_f32_16x16x32_bf16 v[122:125], v[168:171], v[192:195], v[122:125]
	v_mfma_f32_16x16x32_bf16 v[110:113], v[160:163], v[200:203], v[110:113]
	v_mfma_f32_16x16x32_bf16 v[106:109], v[168:171], v[200:203], v[106:109]
	v_mfma_f32_16x16x32_bf16 v[94:97], v[160:163], v[208:211], v[94:97]
	v_mfma_f32_16x16x32_bf16 v[90:93], v[168:171], v[208:211], v[90:93]
	v_mfma_f32_16x16x32_bf16 v[78:81], v[160:163], v[216:219], v[78:81]
	v_mfma_f32_16x16x32_bf16 v[74:77], v[168:171], v[216:219], v[74:77]
	v_mfma_f32_16x16x32_bf16 v[126:129], v[164:167], v[196:199], v[126:129]
	v_mfma_f32_16x16x32_bf16 v[122:125], v[172:175], v[196:199], v[122:125]
	v_mfma_f32_16x16x32_bf16 v[110:113], v[164:167], v[204:207], v[110:113]
	v_mfma_f32_16x16x32_bf16 v[106:109], v[172:175], v[204:207], v[106:109]
	v_mfma_f32_16x16x32_bf16 v[94:97], v[164:167], v[212:215], v[94:97]
	v_mfma_f32_16x16x32_bf16 v[90:93], v[172:175], v[212:215], v[90:93]
	v_mfma_f32_16x16x32_bf16 v[78:81], v[164:167], v[220:223], v[78:81]
	v_mfma_f32_16x16x32_bf16 v[74:77], v[172:175], v[220:223], v[74:77]
	s_setprio 0
	s_setprio 1
	v_mfma_f32_16x16x32_bf16 v[118:121], v[176:179], v[192:195], v[118:121]
	v_mfma_f32_16x16x32_bf16 v[114:117], v[184:187], v[192:195], v[114:117]
	v_mfma_f32_16x16x32_bf16 v[102:105], v[176:179], v[200:203], v[102:105]
	v_mfma_f32_16x16x32_bf16 v[98:101], v[184:187], v[200:203], v[98:101]
	v_mfma_f32_16x16x32_bf16 v[86:89], v[176:179], v[208:211], v[86:89]
	v_mfma_f32_16x16x32_bf16 v[82:85], v[184:187], v[208:211], v[82:85]
	v_mfma_f32_16x16x32_bf16 v[70:73], v[176:179], v[216:219], v[70:73]
	v_mfma_f32_16x16x32_bf16 v[66:69], v[184:187], v[216:219], v[66:69]
	v_mfma_f32_16x16x32_bf16 v[118:121], v[180:183], v[196:199], v[118:121]
	v_mfma_f32_16x16x32_bf16 v[114:117], v[188:191], v[196:199], v[114:117]
	v_mfma_f32_16x16x32_bf16 v[102:105], v[180:183], v[204:207], v[102:105]
	v_mfma_f32_16x16x32_bf16 v[98:101], v[188:191], v[204:207], v[98:101]
	v_mfma_f32_16x16x32_bf16 v[86:89], v[180:183], v[212:215], v[86:89]
	v_mfma_f32_16x16x32_bf16 v[82:85], v[188:191], v[212:215], v[82:85]
	v_mfma_f32_16x16x32_bf16 v[70:73], v[180:183], v[220:223], v[70:73]
	v_mfma_f32_16x16x32_bf16 v[66:69], v[188:191], v[220:223], v[66:69]
	s_setprio 0
	s_barrier
	s_add_u32 s36, s34, 0x4000
	s_addc_u32 s37, s35, 0
	s_add_i32 s62, s62, s38
	s_mov_b32 m0, s62
	s_nop 0
	global_load_lds_dwordx4 v134, s[36:37]
	s_add_i32 m0, s62, 0x2000
	s_add_u32 s34, s34, 0x104000
	s_addc_u32 s35, s35, 0
	global_load_lds_dwordx4 v130, s[36:37]
	s_add_i32 s36, s63, s38
	s_mov_b32 m0, s36
	s_nop 0
	global_load_lds_dwordx4 v134, s[34:35]
	s_add_i32 m0, s36, 0x2000
	s_nop 0
	global_load_lds_dwordx4 v130, s[34:35]
	s_mov_b32 m0, s45
	s_nop 0
	global_load_lds_dwordx4 v136, s[30:31]
	s_mov_b32 m0, s46
	s_nop 0
	global_load_lds_dwordx4 v132, s[30:31]
	ds_read_b128 v[192:195], v156 offset:49152
	ds_read_b128 v[196:199], v156 offset:50176
	ds_read_b128 v[200:203], v156 offset:51200
	ds_read_b128 v[204:207], v156 offset:52224
	ds_read_b128 v[208:211], v156 offset:53248
	ds_read_b128 v[212:215], v156 offset:54272
	ds_read_b128 v[216:219], v156 offset:55296
	ds_read_b128 v[220:223], v156 offset:56320
	s_waitcnt vmcnt(8)
	s_waitcnt lgkmcnt(0)
	s_barrier
	s_setprio 1
	s_waitcnt lgkmcnt(0)
	v_mfma_f32_16x16x32_bf16 v[62:65], v[160:163], v[192:195], v[62:65]
	v_mfma_f32_16x16x32_bf16 v[58:61], v[168:171], v[192:195], v[58:61]
	v_mfma_f32_16x16x32_bf16 v[46:49], v[160:163], v[200:203], v[46:49]
	v_mfma_f32_16x16x32_bf16 v[42:45], v[168:171], v[200:203], v[42:45]
	v_mfma_f32_16x16x32_bf16 v[30:33], v[160:163], v[208:211], v[30:33]
	v_mfma_f32_16x16x32_bf16 v[26:29], v[168:171], v[208:211], v[26:29]
	v_mfma_f32_16x16x32_bf16 v[14:17], v[160:163], v[216:219], v[14:17]
	v_mfma_f32_16x16x32_bf16 v[10:13], v[168:171], v[216:219], v[10:13]
	v_mfma_f32_16x16x32_bf16 v[62:65], v[164:167], v[196:199], v[62:65]
	v_mfma_f32_16x16x32_bf16 v[58:61], v[172:175], v[196:199], v[58:61]
	v_mfma_f32_16x16x32_bf16 v[46:49], v[164:167], v[204:207], v[46:49]
	v_mfma_f32_16x16x32_bf16 v[42:45], v[172:175], v[204:207], v[42:45]
	v_mfma_f32_16x16x32_bf16 v[30:33], v[164:167], v[212:215], v[30:33]
	v_mfma_f32_16x16x32_bf16 v[26:29], v[172:175], v[212:215], v[26:29]
	v_mfma_f32_16x16x32_bf16 v[14:17], v[164:167], v[220:223], v[14:17]
	v_mfma_f32_16x16x32_bf16 v[10:13], v[172:175], v[220:223], v[10:13]
	s_setprio 0
	s_setprio 1
	v_mfma_f32_16x16x32_bf16 v[54:57], v[176:179], v[192:195], v[54:57]
	v_mfma_f32_16x16x32_bf16 v[50:53], v[184:187], v[192:195], v[50:53]
	v_mfma_f32_16x16x32_bf16 v[38:41], v[176:179], v[200:203], v[38:41]
	v_mfma_f32_16x16x32_bf16 v[34:37], v[184:187], v[200:203], v[34:37]
	v_mfma_f32_16x16x32_bf16 v[22:25], v[176:179], v[208:211], v[22:25]
	v_mfma_f32_16x16x32_bf16 v[18:21], v[184:187], v[208:211], v[18:21]
	v_mfma_f32_16x16x32_bf16 v[6:9], v[176:179], v[216:219], v[6:9]
	v_mfma_f32_16x16x32_bf16 v[2:5], v[184:187], v[216:219], v[2:5]
	v_mfma_f32_16x16x32_bf16 v[54:57], v[180:183], v[196:199], v[54:57]
	v_mfma_f32_16x16x32_bf16 v[50:53], v[188:191], v[196:199], v[50:53]
	v_mfma_f32_16x16x32_bf16 v[38:41], v[180:183], v[204:207], v[38:41]
	v_mfma_f32_16x16x32_bf16 v[34:37], v[188:191], v[204:207], v[34:37]
	v_mfma_f32_16x16x32_bf16 v[22:25], v[180:183], v[212:215], v[22:25]
	v_mfma_f32_16x16x32_bf16 v[18:21], v[188:191], v[212:215], v[18:21]
	v_mfma_f32_16x16x32_bf16 v[6:9], v[180:183], v[220:223], v[6:9]
	v_mfma_f32_16x16x32_bf16 v[2:5], v[188:191], v[220:223], v[2:5]
	s_setprio 0
	s_barrier
	s_add_i32 s61, s61, 2
	s_add_u32 s28, s28, 0x8000
	s_addc_u32 s29, s29, 0
	s_add_u32 s59, s59, 0x8000
	s_addc_u32 s60, s60, 0
	s_cmp_gt_u32 s61, 61
	s_cbranch_scc0 .LBB0_1215
	s_and_b64 vcc, exec, s[16:17]
	s_cbranch_vccz .LBB0_1218
	s_barrier

.LBB0_1292:
	s_add_u32 s42, s40, 0xffc04000
	s_addc_u32 s43, s41, -1
	s_cmpk_eq_i32 s66, 0xfc
	s_cselect_b32 s46, s29, s42
	s_cselect_b32 s47, s14, s43
	s_cselect_b32 s44, s37, s39
	s_cselect_b32 s45, s27, s65
	s_add_u32 s42, s46, 0x4000
	s_addc_u32 s43, s47, 0
	s_add_i32 m0, s53, 0xc000
	s_nop 0
	global_load_lds_dwordx4 v166, s[40:41]
	s_add_i32 m0, s53, 0xe000
	s_nop 0
	global_load_lds_dwordx4 v168, s[40:41]
	ds_read_b128 v[130:133], v206
	ds_read_b128 v[134:137], v206 offset:1024
	ds_read_b128 v[138:141], v206 offset:2048
	ds_read_b128 v[142:145], v206 offset:3072
	ds_read_b128 v[146:149], v207
	ds_read_b128 v[150:153], v207 offset:1024
	ds_read_b128 v[176:179], v207 offset:2048
	ds_read_b128 v[180:183], v207 offset:3072
	ds_read_b128 v[184:187], v208
	ds_read_b128 v[188:191], v208 offset:1024
	ds_read_b128 v[192:195], v208 offset:2048
	ds_read_b128 v[196:199], v208 offset:3072
	ds_read_b128 v[210:213], v208 offset:4096
	ds_read_b128 v[214:217], v208 offset:5120
	ds_read_b128 v[218:221], v208 offset:6144
	ds_read_b128 v[222:225], v208 offset:7168
	s_waitcnt vmcnt(8)
	s_waitcnt lgkmcnt(0)
	s_barrier
	s_setprio 1
	s_waitcnt lgkmcnt(0)
	v_mfma_f32_16x16x32_bf16 v[126:129], v[130:133], v[184:187], v[126:129]
	v_mfma_f32_16x16x32_bf16 v[122:125], v[138:141], v[184:187], v[122:125]
	v_mfma_f32_16x16x32_bf16 v[110:113], v[130:133], v[192:195], v[110:113]
	v_mfma_f32_16x16x32_bf16 v[106:109], v[138:141], v[192:195], v[106:109]
	v_mfma_f32_16x16x32_bf16 v[94:97], v[130:133], v[210:213], v[94:97]
	v_mfma_f32_16x16x32_bf16 v[90:93], v[138:141], v[210:213], v[90:93]
	v_mfma_f32_16x16x32_bf16 v[78:81], v[130:133], v[218:221], v[78:81]
	v_mfma_f32_16x16x32_bf16 v[74:77], v[138:141], v[218:221], v[74:77]
	v_mfma_f32_16x16x32_bf16 v[126:129], v[134:137], v[188:191], v[126:129]
	v_mfma_f32_16x16x32_bf16 v[122:125], v[142:145], v[188:191], v[122:125]
	v_mfma_f32_16x16x32_bf16 v[110:113], v[134:137], v[196:199], v[110:113]
	v_mfma_f32_16x16x32_bf16 v[106:109], v[142:145], v[196:199], v[106:109]
	v_mfma_f32_16x16x32_bf16 v[94:97], v[134:137], v[214:217], v[94:97]
	v_mfma_f32_16x16x32_bf16 v[90:93], v[142:145], v[214:217], v[90:93]
	v_mfma_f32_16x16x32_bf16 v[78:81], v[134:137], v[222:225], v[78:81]
	v_mfma_f32_16x16x32_bf16 v[74:77], v[142:145], v[222:225], v[74:77]
	s_setprio 0
	s_setprio 1
	v_mfma_f32_16x16x32_bf16 v[118:121], v[146:149], v[184:187], v[118:121]
	v_mfma_f32_16x16x32_bf16 v[114:117], v[176:179], v[184:187], v[114:117]
	v_mfma_f32_16x16x32_bf16 v[102:105], v[146:149], v[192:195], v[102:105]
	v_mfma_f32_16x16x32_bf16 v[98:101], v[176:179], v[192:195], v[98:101]
	v_mfma_f32_16x16x32_bf16 v[86:89], v[146:149], v[210:213], v[86:89]
	v_mfma_f32_16x16x32_bf16 v[82:85], v[176:179], v[210:213], v[82:85]
	v_mfma_f32_16x16x32_bf16 v[70:73], v[146:149], v[218:221], v[70:73]
	v_mfma_f32_16x16x32_bf16 v[66:69], v[176:179], v[218:221], v[66:69]
	v_mfma_f32_16x16x32_bf16 v[118:121], v[150:153], v[188:191], v[118:121]
	v_mfma_f32_16x16x32_bf16 v[114:117], v[180:183], v[188:191], v[114:117]
	v_mfma_f32_16x16x32_bf16 v[102:105], v[150:153], v[196:199], v[102:105]
	v_mfma_f32_16x16x32_bf16 v[98:101], v[180:183], v[196:199], v[98:101]
	v_mfma_f32_16x16x32_bf16 v[86:89], v[150:153], v[214:217], v[86:89]
	v_mfma_f32_16x16x32_bf16 v[82:85], v[180:183], v[214:217], v[82:85]
	v_mfma_f32_16x16x32_bf16 v[70:73], v[150:153], v[222:225], v[70:73]
	v_mfma_f32_16x16x32_bf16 v[66:69], v[180:183], v[222:225], v[66:69]
	s_setprio 0
	s_barrier
	s_add_i32 s67, s62, s52
	s_mov_b32 m0, s67
	s_nop 0
	global_load_lds_dwordx4 v156, s[44:45]
	s_add_i32 m0, s67, 0x2000
	s_add_u32 s68, s44, 0x400000
	s_addc_u32 s69, s45, 0
	s_add_i32 s67, s63, s52
	global_load_lds_dwordx4 v160, s[44:45]
	s_mov_b32 m0, s67
	s_nop 0
	global_load_lds_dwordx4 v156, s[68:69]
	s_add_i32 m0, s67, 0x2000
	s_nop 0
	global_load_lds_dwordx4 v160, s[68:69]
	s_mov_b32 m0, s53
	s_nop 0
	global_load_lds_dwordx4 v154, s[46:47]
	s_mov_b32 m0, s54
	s_nop 0
	global_load_lds_dwordx4 v158, s[46:47]
	ds_read_b128 v[184:187], v208 offset:16384
	ds_read_b128 v[188:191], v208 offset:17408
	ds_read_b128 v[192:195], v208 offset:18432
	ds_read_b128 v[196:199], v208 offset:19456
	ds_read_b128 v[210:213], v208 offset:20480
	ds_read_b128 v[214:217], v208 offset:21504
	ds_read_b128 v[218:221], v208 offset:22528
	ds_read_b128 v[222:225], v208 offset:23552
	s_waitcnt vmcnt(8)
	s_waitcnt lgkmcnt(0)
	s_barrier
	s_setprio 1
	s_waitcnt lgkmcnt(0)
	v_mfma_f32_16x16x32_bf16 v[62:65], v[130:133], v[184:187], v[62:65]
	v_mfma_f32_16x16x32_bf16 v[58:61], v[138:141], v[184:187], v[58:61]
	v_mfma_f32_16x16x32_bf16 v[46:49], v[130:133], v[192:195], v[46:49]
	v_mfma_f32_16x16x32_bf16 v[42:45], v[138:141], v[192:195], v[42:45]
	v_mfma_f32_16x16x32_bf16 v[30:33], v[130:133], v[210:213], v[30:33]
	v_mfma_f32_16x16x32_bf16 v[26:29], v[138:141], v[210:213], v[26:29]
	v_mfma_f32_16x16x32_bf16 v[14:17], v[130:133], v[218:221], v[14:17]
	v_mfma_f32_16x16x32_bf16 v[10:13], v[138:141], v[218:221], v[10:13]
	v_mfma_f32_16x16x32_bf16 v[62:65], v[134:137], v[188:191], v[62:65]
	v_mfma_f32_16x16x32_bf16 v[58:61], v[142:145], v[188:191], v[58:61]
	v_mfma_f32_16x16x32_bf16 v[46:49], v[134:137], v[196:199], v[46:49]
	v_mfma_f32_16x16x32_bf16 v[42:45], v[142:145], v[196:199], v[42:45]
	v_mfma_f32_16x16x32_bf16 v[30:33], v[134:137], v[214:217], v[30:33]
	v_mfma_f32_16x16x32_bf16 v[26:29], v[142:145], v[214:217], v[26:29]
	v_mfma_f32_16x16x32_bf16 v[14:17], v[134:137], v[222:225], v[14:17]
	v_mfma_f32_16x16x32_bf16 v[10:13], v[142:145], v[222:225], v[10:13]
	s_setprio 0
	s_setprio 1
	v_mfma_f32_16x16x32_bf16 v[54:57], v[146:149], v[184:187], v[54:57]
	v_mfma_f32_16x16x32_bf16 v[50:53], v[176:179], v[184:187], v[50:53]
	v_mfma_f32_16x16x32_bf16 v[38:41], v[146:149], v[192:195], v[38:41]
	v_mfma_f32_16x16x32_bf16 v[34:37], v[176:179], v[192:195], v[34:37]
	v_mfma_f32_16x16x32_bf16 v[22:25], v[146:149], v[210:213], v[22:25]
	v_mfma_f32_16x16x32_bf16 v[18:21], v[176:179], v[210:213], v[18:21]
	v_mfma_f32_16x16x32_bf16 v[6:9], v[146:149], v[218:221], v[6:9]
	v_mfma_f32_16x16x32_bf16 v[2:5], v[176:179], v[218:221], v[2:5]
	v_mfma_f32_16x16x32_bf16 v[54:57], v[150:153], v[188:191], v[54:57]
	v_mfma_f32_16x16x32_bf16 v[50:53], v[180:183], v[188:191], v[50:53]
	v_mfma_f32_16x16x32_bf16 v[38:41], v[150:153], v[196:199], v[38:41]
	v_mfma_f32_16x16x32_bf16 v[34:37], v[180:183], v[196:199], v[34:37]
	v_mfma_f32_16x16x32_bf16 v[22:25], v[150:153], v[214:217], v[22:25]
	v_mfma_f32_16x16x32_bf16 v[18:21], v[180:183], v[214:217], v[18:21]
	v_mfma_f32_16x16x32_bf16 v[6:9], v[150:153], v[222:225], v[6:9]
	v_mfma_f32_16x16x32_bf16 v[2:5], v[180:183], v[222:225], v[2:5]
	s_setprio 0
	s_barrier
	s_add_i32 s67, 0, 0x18000
	s_add_i32 s68, 0, 0x1c000
	s_add_u32 s46, s46, 0x400000
	s_addc_u32 s47, s47, 0
	s_mov_b32 m0, s55
	s_nop 0
	global_load_lds_dwordx4 v154, s[46:47]
	s_mov_b32 m0, s56
	s_nop 0
	global_load_lds_dwordx4 v158, s[46:47]
	v_add_u32_e32 v142, s67, v203
	v_add_u32_e32 v162, s68, v203
	ds_read_b128 v[130:133], v142
	ds_read_b128 v[134:137], v142 offset:1024
	ds_read_b128 v[138:141], v142 offset:2048
	ds_read_b128 v[142:145], v142 offset:3072
	ds_read_b128 v[146:149], v162
	ds_read_b128 v[150:153], v162 offset:1024
	ds_read_b128 v[176:179], v162 offset:2048
	ds_read_b128 v[180:183], v162 offset:3072
	ds_read_b128 v[184:187], v208 offset:32768
	ds_read_b128 v[188:191], v208 offset:33792
	ds_read_b128 v[192:195], v208 offset:34816
	ds_read_b128 v[196:199], v208 offset:35840
	ds_read_b128 v[210:213], v208 offset:36864
	ds_read_b128 v[214:217], v208 offset:37888
	ds_read_b128 v[218:221], v208 offset:38912
	ds_read_b128 v[222:225], v208 offset:39936
	s_waitcnt vmcnt(8)
	s_waitcnt lgkmcnt(0)
	s_barrier
	s_setprio 1
	s_waitcnt lgkmcnt(0)
	v_mfma_f32_16x16x32_bf16 v[126:129], v[130:133], v[184:187], v[126:129]
	v_mfma_f32_16x16x32_bf16 v[122:125], v[138:141], v[184:187], v[122:125]
	v_mfma_f32_16x16x32_bf16 v[110:113], v[130:133], v[192:195], v[110:113]
	v_mfma_f32_16x16x32_bf16 v[106:109], v[138:141], v[192:195], v[106:109]
	v_mfma_f32_16x16x32_bf16 v[94:97], v[130:133], v[210:213], v[94:97]
	v_mfma_f32_16x16x32_bf16 v[90:93], v[138:141], v[210:213], v[90:93]
	v_mfma_f32_16x16x32_bf16 v[78:81], v[130:133], v[218:221], v[78:81]
	v_mfma_f32_16x16x32_bf16 v[74:77], v[138:141], v[218:221], v[74:77]
	v_mfma_f32_16x16x32_bf16 v[126:129], v[134:137], v[188:191], v[126:129]
	v_mfma_f32_16x16x32_bf16 v[122:125], v[142:145], v[188:191], v[122:125]
	v_mfma_f32_16x16x32_bf16 v[110:113], v[134:137], v[196:199], v[110:113]
	v_mfma_f32_16x16x32_bf16 v[106:109], v[142:145], v[196:199], v[106:109]
	v_mfma_f32_16x16x32_bf16 v[94:97], v[134:137], v[214:217], v[94:97]
	v_mfma_f32_16x16x32_bf16 v[90:93], v[142:145], v[214:217], v[90:93]
	v_mfma_f32_16x16x32_bf16 v[78:81], v[134:137], v[222:225], v[78:81]
	v_mfma_f32_16x16x32_bf16 v[74:77], v[142:145], v[222:225], v[74:77]
	s_setprio 0
	s_setprio 1
	v_mfma_f32_16x16x32_bf16 v[118:121], v[146:149], v[184:187], v[118:121]
	v_mfma_f32_16x16x32_bf16 v[114:117], v[176:179], v[184:187], v[114:117]
	v_mfma_f32_16x16x32_bf16 v[102:105], v[146:149], v[192:195], v[102:105]
	v_mfma_f32_16x16x32_bf16 v[98:101], v[176:179], v[192:195], v[98:101]
	v_mfma_f32_16x16x32_bf16 v[86:89], v[146:149], v[210:213], v[86:89]
	v_mfma_f32_16x16x32_bf16 v[82:85], v[176:179], v[210:213], v[82:85]
	v_mfma_f32_16x16x32_bf16 v[70:73], v[146:149], v[218:221], v[70:73]
	v_mfma_f32_16x16x32_bf16 v[66:69], v[176:179], v[218:221], v[66:69]
	v_mfma_f32_16x16x32_bf16 v[118:121], v[150:153], v[188:191], v[118:121]
	v_mfma_f32_16x16x32_bf16 v[114:117], v[180:183], v[188:191], v[114:117]
	v_mfma_f32_16x16x32_bf16 v[102:105], v[150:153], v[196:199], v[102:105]
	v_mfma_f32_16x16x32_bf16 v[98:101], v[180:183], v[196:199], v[98:101]
	v_mfma_f32_16x16x32_bf16 v[86:89], v[150:153], v[214:217], v[86:89]
	v_mfma_f32_16x16x32_bf16 v[82:85], v[180:183], v[214:217], v[82:85]
	v_mfma_f32_16x16x32_bf16 v[70:73], v[150:153], v[222:225], v[70:73]
	v_mfma_f32_16x16x32_bf16 v[66:69], v[180:183], v[222:225], v[66:69]
	s_setprio 0
	s_barrier
	s_add_u32 s46, s44, 0x4000
	s_addc_u32 s47, s45, 0
	s_add_i32 s67, s67, s52
	s_mov_b32 m0, s67
	s_nop 0
	global_load_lds_dwordx4 v156, s[46:47]
	s_add_i32 m0, s67, 0x2000
	s_add_u32 s44, s44, 0x404000
	s_addc_u32 s45, s45, 0
	global_load_lds_dwordx4 v160, s[46:47]
	s_add_i32 s46, s68, s52
	s_mov_b32 m0, s46
	s_nop 0
	global_load_lds_dwordx4 v156, s[44:45]
	s_add_i32 m0, s46, 0x2000
	s_nop 0
	global_load_lds_dwordx4 v160, s[44:45]
	s_mov_b32 m0, s60
	s_nop 0
	global_load_lds_dwordx4 v154, s[42:43]
	s_mov_b32 m0, s61
	s_nop 0
	global_load_lds_dwordx4 v158, s[42:43]
	ds_read_b128 v[184:187], v208 offset:49152
	ds_read_b128 v[188:191], v208 offset:50176
	ds_read_b128 v[192:195], v208 offset:51200
	ds_read_b128 v[196:199], v208 offset:52224
	ds_read_b128 v[210:213], v208 offset:53248
	ds_read_b128 v[214:217], v208 offset:54272
	ds_read_b128 v[218:221], v208 offset:55296
	ds_read_b128 v[222:225], v208 offset:56320
	s_waitcnt vmcnt(8)
	s_waitcnt lgkmcnt(0)
	s_barrier
	s_setprio 1
	s_waitcnt lgkmcnt(0)
	v_mfma_f32_16x16x32_bf16 v[62:65], v[130:133], v[184:187], v[62:65]
	v_mfma_f32_16x16x32_bf16 v[58:61], v[138:141], v[184:187], v[58:61]
	v_mfma_f32_16x16x32_bf16 v[46:49], v[130:133], v[192:195], v[46:49]
	v_mfma_f32_16x16x32_bf16 v[42:45], v[138:141], v[192:195], v[42:45]
	v_mfma_f32_16x16x32_bf16 v[30:33], v[130:133], v[210:213], v[30:33]
	v_mfma_f32_16x16x32_bf16 v[26:29], v[138:141], v[210:213], v[26:29]
	v_mfma_f32_16x16x32_bf16 v[14:17], v[130:133], v[218:221], v[14:17]
	v_mfma_f32_16x16x32_bf16 v[10:13], v[138:141], v[218:221], v[10:13]
	v_mfma_f32_16x16x32_bf16 v[62:65], v[134:137], v[188:191], v[62:65]
	v_mfma_f32_16x16x32_bf16 v[58:61], v[142:145], v[188:191], v[58:61]
	v_mfma_f32_16x16x32_bf16 v[46:49], v[134:137], v[196:199], v[46:49]
	v_mfma_f32_16x16x32_bf16 v[42:45], v[142:145], v[196:199], v[42:45]
	v_mfma_f32_16x16x32_bf16 v[30:33], v[134:137], v[214:217], v[30:33]
	v_mfma_f32_16x16x32_bf16 v[26:29], v[142:145], v[214:217], v[26:29]
	v_mfma_f32_16x16x32_bf16 v[14:17], v[134:137], v[222:225], v[14:17]
	v_mfma_f32_16x16x32_bf16 v[10:13], v[142:145], v[222:225], v[10:13]
	s_setprio 0
	s_setprio 1
	v_mfma_f32_16x16x32_bf16 v[54:57], v[146:149], v[184:187], v[54:57]
	v_mfma_f32_16x16x32_bf16 v[50:53], v[176:179], v[184:187], v[50:53]
	v_mfma_f32_16x16x32_bf16 v[38:41], v[146:149], v[192:195], v[38:41]
	v_mfma_f32_16x16x32_bf16 v[34:37], v[176:179], v[192:195], v[34:37]
	v_mfma_f32_16x16x32_bf16 v[22:25], v[146:149], v[210:213], v[22:25]
	v_mfma_f32_16x16x32_bf16 v[18:21], v[176:179], v[210:213], v[18:21]
	v_mfma_f32_16x16x32_bf16 v[6:9], v[146:149], v[218:221], v[6:9]
	v_mfma_f32_16x16x32_bf16 v[2:5], v[176:179], v[218:221], v[2:5]
	v_mfma_f32_16x16x32_bf16 v[54:57], v[150:153], v[188:191], v[54:57]
	v_mfma_f32_16x16x32_bf16 v[50:53], v[180:183], v[188:191], v[50:53]
	v_mfma_f32_16x16x32_bf16 v[38:41], v[150:153], v[196:199], v[38:41]
	v_mfma_f32_16x16x32_bf16 v[34:37], v[180:183], v[196:199], v[34:37]
	v_mfma_f32_16x16x32_bf16 v[22:25], v[150:153], v[214:217], v[22:25]
	v_mfma_f32_16x16x32_bf16 v[18:21], v[180:183], v[214:217], v[18:21]
	v_mfma_f32_16x16x32_bf16 v[6:9], v[150:153], v[222:225], v[6:9]
	v_mfma_f32_16x16x32_bf16 v[2:5], v[180:183], v[222:225], v[2:5]
	s_setprio 0
	s_barrier
	s_add_i32 s66, s66, 2
	s_add_u32 s40, s40, 0x8000
	s_addc_u32 s41, s41, 0
	s_add_u32 s39, s39, 0x8000
	s_addc_u32 s65, s65, 0
	s_cmpk_gt_u32 s66, 0xfd
	s_cbranch_scc0 .LBB0_1292
	s_and_b64 vcc, exec, s[24:25]
	s_cbranch_vccz .LBB0_1295
	s_barrier

.LBB0_1387:
	s_add_u32 s34, s30, 0xfff04000
	s_addc_u32 s35, s31, -1
	s_cmp_eq_u32 s54, 60
	s_cselect_b32 s38, s27, s34
	s_cselect_b32 s39, s21, s35
	s_cselect_b32 s36, s29, s52
	s_cselect_b32 s37, s19, s53
	s_add_u32 s34, s38, 0x4000
	s_addc_u32 s35, s39, 0
	s_add_i32 m0, s40, 0xc000
	s_nop 0
	global_load_lds_dwordx4 v172, s[30:31]
	s_add_i32 m0, s40, 0xe000
	s_nop 0
	global_load_lds_dwordx4 v174, s[30:31]
	ds_read_b128 v[62:65], v189
	ds_read_b128 v[66:69], v189 offset:1024
	ds_read_b128 v[74:77], v189 offset:2048
	ds_read_b128 v[78:81], v189 offset:3072
	ds_read_b128 v[146:149], v195
	ds_read_b128 v[150:153], v195 offset:1024
	ds_read_b128 v[154:157], v195 offset:2048
	ds_read_b128 v[158:161], v195 offset:3072
	ds_read_b128 v[190:193], v197
	ds_read_b128 v[198:201], v197 offset:1024
	ds_read_b128 v[202:205], v197 offset:2048
	ds_read_b128 v[206:209], v197 offset:3072
	ds_read_b128 v[210:213], v197 offset:4096
	ds_read_b128 v[214:217], v197 offset:5120
	ds_read_b128 v[218:221], v197 offset:6144
	ds_read_b128 v[222:225], v197 offset:7168
	s_waitcnt vmcnt(8)
	s_waitcnt lgkmcnt(0)
	s_barrier
	s_setprio 1
	s_waitcnt lgkmcnt(0)
	v_mfma_f32_16x16x32_bf16 v[142:145], v[62:65], v[190:193], v[142:145]
	v_mfma_f32_16x16x32_bf16 v[138:141], v[74:77], v[190:193], v[138:141]
	v_mfma_f32_16x16x32_bf16 v[126:129], v[62:65], v[202:205], v[126:129]
	v_mfma_f32_16x16x32_bf16 v[122:125], v[74:77], v[202:205], v[122:125]
	v_mfma_f32_16x16x32_bf16 v[110:113], v[62:65], v[210:213], v[110:113]
	v_mfma_f32_16x16x32_bf16 v[106:109], v[74:77], v[210:213], v[106:109]
	v_mfma_f32_16x16x32_bf16 v[94:97], v[62:65], v[218:221], v[94:97]
	v_mfma_f32_16x16x32_bf16 v[90:93], v[74:77], v[218:221], v[90:93]
	v_mfma_f32_16x16x32_bf16 v[142:145], v[66:69], v[198:201], v[142:145]
	v_mfma_f32_16x16x32_bf16 v[138:141], v[78:81], v[198:201], v[138:141]
	v_mfma_f32_16x16x32_bf16 v[126:129], v[66:69], v[206:209], v[126:129]
	v_mfma_f32_16x16x32_bf16 v[122:125], v[78:81], v[206:209], v[122:125]
	v_mfma_f32_16x16x32_bf16 v[110:113], v[66:69], v[214:217], v[110:113]
	v_mfma_f32_16x16x32_bf16 v[106:109], v[78:81], v[214:217], v[106:109]
	v_mfma_f32_16x16x32_bf16 v[94:97], v[66:69], v[222:225], v[94:97]
	v_mfma_f32_16x16x32_bf16 v[90:93], v[78:81], v[222:225], v[90:93]
	s_setprio 0
	s_setprio 1
	v_mfma_f32_16x16x32_bf16 v[134:137], v[146:149], v[190:193], v[134:137]
	v_mfma_f32_16x16x32_bf16 v[130:133], v[154:157], v[190:193], v[130:133]
	v_mfma_f32_16x16x32_bf16 v[118:121], v[146:149], v[202:205], v[118:121]
	v_mfma_f32_16x16x32_bf16 v[114:117], v[154:157], v[202:205], v[114:117]
	v_mfma_f32_16x16x32_bf16 v[102:105], v[146:149], v[210:213], v[102:105]
	v_mfma_f32_16x16x32_bf16 v[98:101], v[154:157], v[210:213], v[98:101]
	v_mfma_f32_16x16x32_bf16 v[86:89], v[146:149], v[218:221], v[86:89]
	v_mfma_f32_16x16x32_bf16 v[82:85], v[154:157], v[218:221], v[82:85]
	v_mfma_f32_16x16x32_bf16 v[134:137], v[150:153], v[198:201], v[134:137]
	v_mfma_f32_16x16x32_bf16 v[130:133], v[158:161], v[198:201], v[130:133]
	v_mfma_f32_16x16x32_bf16 v[118:121], v[150:153], v[206:209], v[118:121]
	v_mfma_f32_16x16x32_bf16 v[114:117], v[158:161], v[206:209], v[114:117]
	v_mfma_f32_16x16x32_bf16 v[102:105], v[150:153], v[214:217], v[102:105]
	v_mfma_f32_16x16x32_bf16 v[98:101], v[158:161], v[214:217], v[98:101]
	v_mfma_f32_16x16x32_bf16 v[86:89], v[150:153], v[222:225], v[86:89]
	v_mfma_f32_16x16x32_bf16 v[82:85], v[158:161], v[222:225], v[82:85]
	s_setprio 0
	s_barrier
	s_add_i32 s55, s50, s33
	s_mov_b32 m0, s55
	s_nop 0
	global_load_lds_dwordx4 v166, s[36:37]
	s_add_i32 m0, s55, 0x2000
	s_add_u32 s56, s36, 0x100000
	s_addc_u32 s57, s37, 0
	s_add_i32 s55, s51, s33
	global_load_lds_dwordx4 v162, s[36:37]
	s_mov_b32 m0, s55
	s_nop 0
	global_load_lds_dwordx4 v166, s[56:57]
	s_add_i32 m0, s55, 0x2000
	s_nop 0
	global_load_lds_dwordx4 v162, s[56:57]
	s_mov_b32 m0, s40
	s_nop 0
	global_load_lds_dwordx4 v168, s[38:39]
	s_mov_b32 m0, s41
	s_nop 0
	global_load_lds_dwordx4 v164, s[38:39]
	ds_read_b128 v[190:193], v197 offset:16384
	ds_read_b128 v[198:201], v197 offset:17408
	ds_read_b128 v[202:205], v197 offset:18432
	ds_read_b128 v[206:209], v197 offset:19456
	ds_read_b128 v[210:213], v197 offset:20480
	ds_read_b128 v[214:217], v197 offset:21504
	ds_read_b128 v[218:221], v197 offset:22528
	ds_read_b128 v[222:225], v197 offset:23552
	s_waitcnt vmcnt(8)
	s_waitcnt lgkmcnt(0)
	s_barrier
	s_setprio 1
	s_waitcnt lgkmcnt(0)
	v_mfma_f32_16x16x32_bf16 v[70:73], v[62:65], v[190:193], v[70:73]
	v_mfma_f32_16x16x32_bf16 v[58:61], v[74:77], v[190:193], v[58:61]
	v_mfma_f32_16x16x32_bf16 v[46:49], v[62:65], v[202:205], v[46:49]
	v_mfma_f32_16x16x32_bf16 v[42:45], v[74:77], v[202:205], v[42:45]
	v_mfma_f32_16x16x32_bf16 v[30:33], v[62:65], v[210:213], v[30:33]
	v_mfma_f32_16x16x32_bf16 v[26:29], v[74:77], v[210:213], v[26:29]
	v_mfma_f32_16x16x32_bf16 v[14:17], v[62:65], v[218:221], v[14:17]
	v_mfma_f32_16x16x32_bf16 v[10:13], v[74:77], v[218:221], v[10:13]
	v_mfma_f32_16x16x32_bf16 v[70:73], v[66:69], v[198:201], v[70:73]
	v_mfma_f32_16x16x32_bf16 v[58:61], v[78:81], v[198:201], v[58:61]
	v_mfma_f32_16x16x32_bf16 v[46:49], v[66:69], v[206:209], v[46:49]
	v_mfma_f32_16x16x32_bf16 v[42:45], v[78:81], v[206:209], v[42:45]
	v_mfma_f32_16x16x32_bf16 v[30:33], v[66:69], v[214:217], v[30:33]
	v_mfma_f32_16x16x32_bf16 v[26:29], v[78:81], v[214:217], v[26:29]
	v_mfma_f32_16x16x32_bf16 v[14:17], v[66:69], v[222:225], v[14:17]
	v_mfma_f32_16x16x32_bf16 v[10:13], v[78:81], v[222:225], v[10:13]
	s_setprio 0
	s_setprio 1
	v_mfma_f32_16x16x32_bf16 v[54:57], v[146:149], v[190:193], v[54:57]
	v_mfma_f32_16x16x32_bf16 v[50:53], v[154:157], v[190:193], v[50:53]
	v_mfma_f32_16x16x32_bf16 v[38:41], v[146:149], v[202:205], v[38:41]
	v_mfma_f32_16x16x32_bf16 v[34:37], v[154:157], v[202:205], v[34:37]
	v_mfma_f32_16x16x32_bf16 v[22:25], v[146:149], v[210:213], v[22:25]
	v_mfma_f32_16x16x32_bf16 v[18:21], v[154:157], v[210:213], v[18:21]
	v_mfma_f32_16x16x32_bf16 v[6:9], v[146:149], v[218:221], v[6:9]
	v_mfma_f32_16x16x32_bf16 v[2:5], v[154:157], v[218:221], v[2:5]
	v_mfma_f32_16x16x32_bf16 v[54:57], v[150:153], v[198:201], v[54:57]
	v_mfma_f32_16x16x32_bf16 v[50:53], v[158:161], v[198:201], v[50:53]
	v_mfma_f32_16x16x32_bf16 v[38:41], v[150:153], v[206:209], v[38:41]
	v_mfma_f32_16x16x32_bf16 v[34:37], v[158:161], v[206:209], v[34:37]
	v_mfma_f32_16x16x32_bf16 v[22:25], v[150:153], v[214:217], v[22:25]
	v_mfma_f32_16x16x32_bf16 v[18:21], v[158:161], v[214:217], v[18:21]
	v_mfma_f32_16x16x32_bf16 v[6:9], v[150:153], v[222:225], v[6:9]
	v_mfma_f32_16x16x32_bf16 v[2:5], v[158:161], v[222:225], v[2:5]
	s_setprio 0
	s_barrier
	s_add_i32 s55, 0, 0x18000
	s_add_i32 s56, 0, 0x1c000
	s_add_u32 s38, s38, 0x100000
	s_addc_u32 s39, s39, 0
	s_mov_b32 m0, s42
	s_nop 0
	global_load_lds_dwordx4 v168, s[38:39]
	s_mov_b32 m0, s43
	s_nop 0
	global_load_lds_dwordx4 v164, s[38:39]
	v_add_u32_e32 v78, s55, v187
	v_add_u32_e32 v158, s56, v187
	ds_read_b128 v[62:65], v78
	ds_read_b128 v[66:69], v78 offset:1024
	ds_read_b128 v[74:77], v78 offset:2048
	ds_read_b128 v[78:81], v78 offset:3072
	ds_read_b128 v[146:149], v158
	ds_read_b128 v[150:153], v158 offset:1024
	ds_read_b128 v[154:157], v158 offset:2048
	ds_read_b128 v[158:161], v158 offset:3072
	ds_read_b128 v[190:193], v197 offset:32768
	ds_read_b128 v[198:201], v197 offset:33792
	ds_read_b128 v[202:205], v197 offset:34816
	ds_read_b128 v[206:209], v197 offset:35840
	ds_read_b128 v[210:213], v197 offset:36864
	ds_read_b128 v[214:217], v197 offset:37888
	ds_read_b128 v[218:221], v197 offset:38912
	ds_read_b128 v[222:225], v197 offset:39936
	s_waitcnt vmcnt(8)
	s_waitcnt lgkmcnt(0)
	s_barrier
	s_setprio 1
	s_waitcnt lgkmcnt(0)
	v_mfma_f32_16x16x32_bf16 v[142:145], v[62:65], v[190:193], v[142:145]
	v_mfma_f32_16x16x32_bf16 v[138:141], v[74:77], v[190:193], v[138:141]
	v_mfma_f32_16x16x32_bf16 v[126:129], v[62:65], v[202:205], v[126:129]
	v_mfma_f32_16x16x32_bf16 v[122:125], v[74:77], v[202:205], v[122:125]
	v_mfma_f32_16x16x32_bf16 v[110:113], v[62:65], v[210:213], v[110:113]
	v_mfma_f32_16x16x32_bf16 v[106:109], v[74:77], v[210:213], v[106:109]
	v_mfma_f32_16x16x32_bf16 v[94:97], v[62:65], v[218:221], v[94:97]
	v_mfma_f32_16x16x32_bf16 v[90:93], v[74:77], v[218:221], v[90:93]
	v_mfma_f32_16x16x32_bf16 v[142:145], v[66:69], v[198:201], v[142:145]
	v_mfma_f32_16x16x32_bf16 v[138:141], v[78:81], v[198:201], v[138:141]
	v_mfma_f32_16x16x32_bf16 v[126:129], v[66:69], v[206:209], v[126:129]
	v_mfma_f32_16x16x32_bf16 v[122:125], v[78:81], v[206:209], v[122:125]
	v_mfma_f32_16x16x32_bf16 v[110:113], v[66:69], v[214:217], v[110:113]
	v_mfma_f32_16x16x32_bf16 v[106:109], v[78:81], v[214:217], v[106:109]
	v_mfma_f32_16x16x32_bf16 v[94:97], v[66:69], v[222:225], v[94:97]
	v_mfma_f32_16x16x32_bf16 v[90:93], v[78:81], v[222:225], v[90:93]
	s_setprio 0
	s_setprio 1
	v_mfma_f32_16x16x32_bf16 v[134:137], v[146:149], v[190:193], v[134:137]
	v_mfma_f32_16x16x32_bf16 v[130:133], v[154:157], v[190:193], v[130:133]
	v_mfma_f32_16x16x32_bf16 v[118:121], v[146:149], v[202:205], v[118:121]
	v_mfma_f32_16x16x32_bf16 v[114:117], v[154:157], v[202:205], v[114:117]
	v_mfma_f32_16x16x32_bf16 v[102:105], v[146:149], v[210:213], v[102:105]
	v_mfma_f32_16x16x32_bf16 v[98:101], v[154:157], v[210:213], v[98:101]
	v_mfma_f32_16x16x32_bf16 v[86:89], v[146:149], v[218:221], v[86:89]
	v_mfma_f32_16x16x32_bf16 v[82:85], v[154:157], v[218:221], v[82:85]
	v_mfma_f32_16x16x32_bf16 v[134:137], v[150:153], v[198:201], v[134:137]
	v_mfma_f32_16x16x32_bf16 v[130:133], v[158:161], v[198:201], v[130:133]
	v_mfma_f32_16x16x32_bf16 v[118:121], v[150:153], v[206:209], v[118:121]
	v_mfma_f32_16x16x32_bf16 v[114:117], v[158:161], v[206:209], v[114:117]
	v_mfma_f32_16x16x32_bf16 v[102:105], v[150:153], v[214:217], v[102:105]
	v_mfma_f32_16x16x32_bf16 v[98:101], v[158:161], v[214:217], v[98:101]
	v_mfma_f32_16x16x32_bf16 v[86:89], v[150:153], v[222:225], v[86:89]
	v_mfma_f32_16x16x32_bf16 v[82:85], v[158:161], v[222:225], v[82:85]
	s_setprio 0
	s_barrier
	s_add_u32 s38, s36, 0x4000
	s_addc_u32 s39, s37, 0
	s_add_i32 s55, s55, s33
	s_mov_b32 m0, s55
	s_nop 0
	global_load_lds_dwordx4 v166, s[38:39]
	s_add_i32 m0, s55, 0x2000
	s_add_u32 s36, s36, 0x104000
	s_addc_u32 s37, s37, 0
	global_load_lds_dwordx4 v162, s[38:39]
	s_add_i32 s38, s56, s33
	s_mov_b32 m0, s38
	s_nop 0
	global_load_lds_dwordx4 v166, s[36:37]
	s_add_i32 m0, s38, 0x2000
	s_nop 0
	global_load_lds_dwordx4 v162, s[36:37]
	s_mov_b32 m0, s46
	s_nop 0
	global_load_lds_dwordx4 v168, s[34:35]
	s_mov_b32 m0, s47
	s_nop 0
	global_load_lds_dwordx4 v164, s[34:35]
	ds_read_b128 v[190:193], v197 offset:49152
	ds_read_b128 v[198:201], v197 offset:50176
	ds_read_b128 v[202:205], v197 offset:51200
	ds_read_b128 v[206:209], v197 offset:52224
	ds_read_b128 v[210:213], v197 offset:53248
	ds_read_b128 v[214:217], v197 offset:54272
	ds_read_b128 v[218:221], v197 offset:55296
	ds_read_b128 v[222:225], v197 offset:56320
	s_waitcnt vmcnt(8)
	s_waitcnt lgkmcnt(0)
	s_barrier
	s_setprio 1
	s_waitcnt lgkmcnt(0)
	v_mfma_f32_16x16x32_bf16 v[70:73], v[62:65], v[190:193], v[70:73]
	v_mfma_f32_16x16x32_bf16 v[58:61], v[74:77], v[190:193], v[58:61]
	v_mfma_f32_16x16x32_bf16 v[46:49], v[62:65], v[202:205], v[46:49]
	v_mfma_f32_16x16x32_bf16 v[42:45], v[74:77], v[202:205], v[42:45]
	v_mfma_f32_16x16x32_bf16 v[30:33], v[62:65], v[210:213], v[30:33]
	v_mfma_f32_16x16x32_bf16 v[26:29], v[74:77], v[210:213], v[26:29]
	v_mfma_f32_16x16x32_bf16 v[14:17], v[62:65], v[218:221], v[14:17]
	v_mfma_f32_16x16x32_bf16 v[10:13], v[74:77], v[218:221], v[10:13]
	v_mfma_f32_16x16x32_bf16 v[70:73], v[66:69], v[198:201], v[70:73]
	v_mfma_f32_16x16x32_bf16 v[58:61], v[78:81], v[198:201], v[58:61]
	v_mfma_f32_16x16x32_bf16 v[46:49], v[66:69], v[206:209], v[46:49]
	v_mfma_f32_16x16x32_bf16 v[42:45], v[78:81], v[206:209], v[42:45]
	v_mfma_f32_16x16x32_bf16 v[30:33], v[66:69], v[214:217], v[30:33]
	v_mfma_f32_16x16x32_bf16 v[26:29], v[78:81], v[214:217], v[26:29]
	v_mfma_f32_16x16x32_bf16 v[14:17], v[66:69], v[222:225], v[14:17]
	v_mfma_f32_16x16x32_bf16 v[10:13], v[78:81], v[222:225], v[10:13]
	s_setprio 0
	s_setprio 1
	v_mfma_f32_16x16x32_bf16 v[54:57], v[146:149], v[190:193], v[54:57]
	v_mfma_f32_16x16x32_bf16 v[50:53], v[154:157], v[190:193], v[50:53]
	v_mfma_f32_16x16x32_bf16 v[38:41], v[146:149], v[202:205], v[38:41]
	v_mfma_f32_16x16x32_bf16 v[34:37], v[154:157], v[202:205], v[34:37]
	v_mfma_f32_16x16x32_bf16 v[22:25], v[146:149], v[210:213], v[22:25]
	v_mfma_f32_16x16x32_bf16 v[18:21], v[154:157], v[210:213], v[18:21]
	v_mfma_f32_16x16x32_bf16 v[6:9], v[146:149], v[218:221], v[6:9]
	v_mfma_f32_16x16x32_bf16 v[2:5], v[154:157], v[218:221], v[2:5]
	v_mfma_f32_16x16x32_bf16 v[54:57], v[150:153], v[198:201], v[54:57]
	v_mfma_f32_16x16x32_bf16 v[50:53], v[158:161], v[198:201], v[50:53]
	v_mfma_f32_16x16x32_bf16 v[38:41], v[150:153], v[206:209], v[38:41]
	v_mfma_f32_16x16x32_bf16 v[34:37], v[158:161], v[206:209], v[34:37]
	v_mfma_f32_16x16x32_bf16 v[22:25], v[150:153], v[214:217], v[22:25]
	v_mfma_f32_16x16x32_bf16 v[18:21], v[158:161], v[214:217], v[18:21]
	v_mfma_f32_16x16x32_bf16 v[6:9], v[150:153], v[222:225], v[6:9]
	v_mfma_f32_16x16x32_bf16 v[2:5], v[158:161], v[222:225], v[2:5]
	s_setprio 0
	s_barrier
	s_add_i32 s54, s54, 2
	s_add_u32 s30, s30, 0x8000
	s_addc_u32 s31, s31, 0
	s_add_u32 s52, s52, 0x8000
	s_addc_u32 s53, s53, 0
	s_cmp_gt_u32 s54, 61
	s_cbranch_scc0 .LBB0_1387
	s_and_b64 vcc, exec, s[12:13]
	s_cbranch_vccz .LBB0_1390
	s_barrier
